# next-unit L2 prefetch extended to gdn/conf halo rows and gdn beta/decay logits, on top of hand-written gdn stages + single-counter barrier
# speedup vs baseline: 1.0004x; 1.0004x over previous
; #define LAS __attribute__((address_space(3)))
; __device__ __forceinline__ void gdn_unit(const Ctx& X, LAS unsigned char* hl, int b, int c, int h, int tid_h, int w4, int lane, int layer) {
;     ...
;         const float G63 = Gs[63];
; #pragma unroll
;         for (int rs = 0; rs < 2; ++rs) {
;             const int i = i0 + 32 * rs;
;             const float bi = Bs[i], Gi = Gs[i];
;             float y[3][8];
; #pragma unroll
;             for (int tn = 0; tn < 3; ++tn) {
; #pragma unroll
;                 for (int e = 0; e < 8; ++e) y[tn][e] = 0.f;
; #pragma unroll
;                 for (int k = 0; k < 4; ++k) { float x8[8]; unpack8(*(const LAS u32x4*)(RAW + (tn * 67 + i + k) * 64 + cseg * 8), x8);
;                     y[tn][0] += wq[tn][k][0].x * x8[0]; y[tn][1] += wq[tn][k][0].y * x8[1]; y[tn][2] += wq[tn][k][0].z * x8[2]; y[tn][3] += wq[tn][k][0].w * x8[3];
;                     y[tn][4] += wq[tn][k][1].x * x8[4]; y[tn][5] += wq[tn][k][1].y * x8[5]; y[tn][6] += wq[tn][k][1].z * x8[6]; y[tn][7] += wq[tn][k][1].w * x8[7]; }
.LpfG_done:
	v_add_u32_e32 v193, v182, v156
	v_cndmask_b32_e32 v102, v230, v102, vcc
	v_lshlrev_b32_e32 v197, 2, v102
	v_xor_b32_e32 v102, 2, v230
	v_cmp_lt_i32_e32 vcc, v102, v103
	v_add_u32_e32 v192, v189, v156
	v_add_u32_e32 v155, v183, v156
	v_add_u32_e32 v133, v181, v156
	v_lshl_add_u32 v156, v191, 7, v135
	ds_read_b32 v194, v185 offset:252
	v_cndmask_b32_e32 v102, v230, v102, vcc
	ds_read_b128 v[106:109], v156
	ds_read_b128 v[112:115], v156 offset:128
	v_lshlrev_b32_e32 v196, 2, v102
	v_xor_b32_e32 v102, 4, v230
	v_cmp_lt_i32_e32 vcc, v102, v103
	s_waitcnt lgkmcnt(1)
	v_lshlrev_b32_e32 v104, 16, v106
	s_waitcnt lgkmcnt(0)
	v_lshlrev_b32_e32 v105, 16, v112
	v_cndmask_b32_e32 v102, v230, v102, vcc
	v_lshlrev_b32_e32 v195, 2, v102
	v_lshlrev_b32_e32 v102, 2, v191
	v_add_u32_e32 v198, v188, v102
	v_add_u32_e32 v199, v185, v102
	v_mov_b32_e32 v102, v66
	v_mov_b32_e32 v103, v74
	v_pk_mul_f32 v[134:135], v[102:103], v[104:105]
	v_and_b32_e32 v105, 0xffff0000, v112
	v_and_b32_e32 v104, 0xffff0000, v106
	v_mov_b32_e32 v74, v67
	v_pk_mul_f32 v[136:137], v[74:75], v[104:105]
	v_lshlrev_b32_e32 v105, 16, v107
	v_lshlrev_b32_e32 v104, 16, v113
	v_mov_b32_e32 v66, v76
	v_mov_b32_e32 v67, v68
	ds_read_b32 v200, v198
	ds_read_b32 v201, v199
	v_pk_mul_f32 v[118:119], v[66:67], v[104:105]
	v_and_b32_e32 v105, 0xffff0000, v107
	v_and_b32_e32 v104, 0xffff0000, v113
	v_mov_b32_e32 v68, v77
	ds_read_b128 v[122:125], v156 offset:256
	ds_read_b128 v[126:129], v156 offset:384
	v_pk_mul_f32 v[120:121], v[68:69], v[104:105]
	v_lshlrev_b32_e32 v77, 16, v114
	v_lshlrev_b32_e32 v76, 16, v108
	v_mov_b32_e32 v104, v58
	v_mov_b32_e32 v105, v98
	v_pk_mul_f32 v[110:111], v[104:105], v[76:77]
	v_and_b32_e32 v77, 0xffff0000, v108
	v_and_b32_e32 v76, 0xffff0000, v114
	v_mov_b32_e32 v58, v99
	v_pk_mul_f32 v[112:113], v[58:59], v[76:77]
	v_lshlrev_b32_e32 v99, 16, v109
	v_lshlrev_b32_e32 v98, 16, v115
	v_mov_b32_e32 v76, v100
	v_mov_b32_e32 v77, v60
	v_pk_mul_f32 v[106:107], v[76:77], v[98:99]
	v_and_b32_e32 v99, 0xffff0000, v109
	v_and_b32_e32 v98, 0xffff0000, v115
	v_mov_b32_e32 v60, v101
	v_pk_mul_f32 v[108:109], v[60:61], v[98:99]
	s_waitcnt lgkmcnt(0)
	v_lshlrev_b32_e32 v101, 16, v126
	v_lshlrev_b32_e32 v100, 16, v122
	v_mov_b32_e32 v98, v62
	v_mov_b32_e32 v99, v70
	v_pk_mul_f32 v[150:151], v[98:99], v[100:101]
	v_and_b32_e32 v101, 0xffff0000, v126
	v_and_b32_e32 v100, 0xffff0000, v122
	v_mov_b32_e32 v70, v63
	v_pk_mul_f32 v[162:163], v[70:71], v[100:101]
	v_lshlrev_b32_e32 v101, 16, v123
	v_lshlrev_b32_e32 v100, 16, v127
	v_mov_b32_e32 v62, v72
	v_mov_b32_e32 v63, v64
	v_pk_mul_f32 v[138:139], v[62:63], v[100:101]
	v_and_b32_e32 v101, 0xffff0000, v123
	v_and_b32_e32 v100, 0xffff0000, v127
	v_mov_b32_e32 v64, v73
	ds_read_b128 v[144:147], v156 offset:8576
	ds_read_b128 v[164:167], v156 offset:8704
	v_pk_mul_f32 v[142:143], v[64:65], v[100:101]
	v_lshlrev_b32_e32 v73, 16, v128
	v_lshlrev_b32_e32 v72, 16, v124
	v_mov_b32_e32 v100, v54
	v_mov_b32_e32 v101, v94
	v_pk_mul_f32 v[122:123], v[100:101], v[72:73]
	v_and_b32_e32 v73, 0xffff0000, v124
	v_and_b32_e32 v72, 0xffff0000, v128
	v_mov_b32_e32 v54, v95
	v_pk_mul_f32 v[126:127], v[54:55], v[72:73]
	v_lshlrev_b32_e32 v95, 16, v125
	v_lshlrev_b32_e32 v94, 16, v129
	v_mov_b32_e32 v72, v96
	v_mov_b32_e32 v73, v56
	v_pk_mul_f32 v[114:115], v[72:73], v[94:95]
	v_and_b32_e32 v95, 0xffff0000, v125
	v_and_b32_e32 v94, 0xffff0000, v129
	v_mov_b32_e32 v56, v97
	v_pk_mul_f32 v[116:117], v[56:57], v[94:95]
	s_waitcnt lgkmcnt(0)
	v_lshlrev_b32_e32 v97, 16, v164
	v_lshlrev_b32_e32 v96, 16, v144
	v_mov_b32_e32 v94, v46
	v_mov_b32_e32 v95, v50
	v_pk_mul_f32 v[168:169], v[94:95], v[96:97]
	v_and_b32_e32 v97, 0xffff0000, v164
	v_and_b32_e32 v96, 0xffff0000, v144
	v_mov_b32_e32 v50, v47
	v_pk_mul_f32 v[170:171], v[50:51], v[96:97]
	v_lshlrev_b32_e32 v97, 16, v145
	v_lshlrev_b32_e32 v96, 16, v165
	v_mov_b32_e32 v46, v52
	v_mov_b32_e32 v47, v48
	v_pk_mul_f32 v[148:149], v[46:47], v[96:97]
	v_and_b32_e32 v97, 0xffff0000, v145
	v_and_b32_e32 v96, 0xffff0000, v165
	v_mov_b32_e32 v48, v53
	ds_read_b128 v[202:205], v156 offset:8832
	ds_read_b128 v[206:209], v156 offset:8960
	v_pk_mul_f32 v[152:153], v[48:49], v[96:97]
	v_lshlrev_b32_e32 v53, 16, v166
	v_lshlrev_b32_e32 v52, 16, v146
	v_mov_b32_e32 v96, v38
	v_mov_b32_e32 v97, v90
	v_pk_mul_f32 v[140:141], v[96:97], v[52:53]
	v_and_b32_e32 v53, 0xffff0000, v146
	v_and_b32_e32 v52, 0xffff0000, v166
	v_mov_b32_e32 v38, v91
	v_pk_mul_f32 v[144:145], v[38:39], v[52:53]
	v_lshlrev_b32_e32 v91, 16, v147
	v_lshlrev_b32_e32 v90, 16, v167
	v_mov_b32_e32 v52, v92
	v_mov_b32_e32 v53, v40
	v_pk_mul_f32 v[124:125], v[52:53], v[90:91]
	v_and_b32_e32 v91, 0xffff0000, v147
	v_and_b32_e32 v90, 0xffff0000, v167
	v_mov_b32_e32 v40, v93
	v_pk_mul_f32 v[128:129], v[40:41], v[90:91]
	s_waitcnt lgkmcnt(0)
	v_lshlrev_b32_e32 v93, 16, v206
	v_lshlrev_b32_e32 v92, 16, v202
	v_mov_b32_e32 v90, v34
	v_mov_b32_e32 v91, v42
	v_pk_mul_f32 v[176:177], v[90:91], v[92:93]
	v_and_b32_e32 v93, 0xffff0000, v206
	v_and_b32_e32 v92, 0xffff0000, v202
	v_mov_b32_e32 v42, v35
	v_pk_mul_f32 v[178:179], v[42:43], v[92:93]
	v_lshlrev_b32_e32 v93, 16, v203
	v_lshlrev_b32_e32 v92, 16, v207
	v_mov_b32_e32 v34, v44
	v_mov_b32_e32 v35, v36
	v_pk_mul_f32 v[172:173], v[34:35], v[92:93]
	v_and_b32_e32 v93, 0xffff0000, v203
	v_and_b32_e32 v92, 0xffff0000, v207
	v_mov_b32_e32 v36, v45
	ds_read_b128 v[210:213], v156 offset:17152
	ds_read_b128 v[214:217], v156 offset:17280
	v_pk_mul_f32 v[174:175], v[36:37], v[92:93]
	v_lshlrev_b32_e32 v45, 16, v208
	v_lshlrev_b32_e32 v44, 16, v204
	v_mov_b32_e32 v92, v30
	v_mov_b32_e32 v93, v86
	v_pk_mul_f32 v[164:165], v[92:93], v[44:45]
	v_and_b32_e32 v45, 0xffff0000, v204
	v_and_b32_e32 v44, 0xffff0000, v208
	v_mov_b32_e32 v30, v87
	v_pk_mul_f32 v[166:167], v[30:31], v[44:45]
	v_lshlrev_b32_e32 v87, 16, v205
	v_lshlrev_b32_e32 v86, 16, v209
	v_mov_b32_e32 v44, v88
	v_mov_b32_e32 v45, v32
	v_pk_mul_f32 v[146:147], v[44:45], v[86:87]
	v_and_b32_e32 v87, 0xffff0000, v205
	v_and_b32_e32 v86, 0xffff0000, v209
	v_mov_b32_e32 v32, v89
	v_pk_mul_f32 v[88:89], v[32:33], v[86:87]
	s_waitcnt lgkmcnt(0)
; #define LAS __attribute__((address_space(3)))
; __device__ __forceinline__ float silu_acc(float x) { return x * frcp(1.0f + fexp(-x)); }
; __device__ __forceinline__ void gdn_unit(const Ctx& X, LAS unsigned char* hl, int b, int c, int h, int tid_h, int w4, int lane, int layer) {
;     ...
;             for (int tn = 0; tn < 3; ++tn) {
; #pragma unroll
;                 for (int e = 0; e < 8; ++e) y[tn][e] = 0.f;
; #pragma unroll
;                 for (int k = 0; k < 4; ++k) { float x8[8]; unpack8(*(const LAS u32x4*)(RAW + (tn * 67 + i + k) * 64 + cseg * 8), x8);
;                     y[tn][0] += wq[tn][k][0].x * x8[0]; y[tn][1] += wq[tn][k][0].y * x8[1]; y[tn][2] += wq[tn][k][0].z * x8[2]; y[tn][3] += wq[tn][k][0].w * x8[3];
;                     y[tn][4] += wq[tn][k][1].x * x8[4]; y[tn][5] += wq[tn][k][1].y * x8[5]; y[tn][6] += wq[tn][k][1].z * x8[6]; y[tn][7] += wq[tn][k][1].w * x8[7]; }
; #pragma unroll
;                 for (int e = 0; e < 8; ++e) y[tn][e] = silu_acc(y[tn][e]);
;             }
	v_lshlrev_b32_e32 v203, 16, v214
	v_lshlrev_b32_e32 v202, 16, v210
	v_mov_b32_e32 v86, v22
	v_mov_b32_e32 v87, v26
	v_pk_mul_f32 v[202:203], v[86:87], v[202:203]
	v_mov_b32_e32 v26, v23
	v_add_f32_e32 v22, 0, v202
	v_add_f32_e32 v218, v22, v203
	v_and_b32_e32 v203, 0xffff0000, v214
	v_and_b32_e32 v202, 0xffff0000, v210
	v_pk_mul_f32 v[22:23], v[26:27], v[202:203]
	v_lshlrev_b32_e32 v203, 16, v211
	v_add_f32_e32 v22, 0, v22
	v_add_f32_e32 v214, v22, v23
	v_lshlrev_b32_e32 v202, 16, v215
	v_mov_b32_e32 v22, v28
	v_mov_b32_e32 v23, v24
	v_pk_mul_f32 v[202:203], v[22:23], v[202:203]
	v_and_b32_e32 v210, 0xffff0000, v217
	v_add_f32_e32 v24, 0, v203
	v_add_f32_e32 v219, v202, v24
	v_and_b32_e32 v203, 0xffff0000, v211
	v_and_b32_e32 v202, 0xffff0000, v215
	v_mov_b32_e32 v24, v29
	v_pk_mul_f32 v[28:29], v[24:25], v[202:203]
	v_lshlrev_b32_e32 v203, 16, v216
	v_add_f32_e32 v29, 0, v29
	v_add_f32_e32 v215, v28, v29
	v_lshlrev_b32_e32 v202, 16, v212
	v_mov_b32_e32 v28, v14
	v_mov_b32_e32 v29, v82
	v_pk_mul_f32 v[202:203], v[28:29], v[202:203]
	v_and_b32_e32 v211, 0xffff0000, v213
	v_add_f32_e32 v14, 0, v202
	v_add_f32_e32 v220, v14, v203
	v_and_b32_e32 v203, 0xffff0000, v212
	v_and_b32_e32 v202, 0xffff0000, v216
	v_mov_b32_e32 v14, v83
	v_pk_mul_f32 v[82:83], v[14:15], v[202:203]
	v_lshlrev_b32_e32 v203, 16, v213
	v_add_f32_e32 v83, 0, v83
	v_add_f32_e32 v212, v82, v83
	v_lshlrev_b32_e32 v202, 16, v217
	v_mov_b32_e32 v82, v84
	v_mov_b32_e32 v83, v16
	v_pk_mul_f32 v[202:203], v[82:83], v[202:203]
	s_mov_b32 s4, 0x358637bd
	v_add_f32_e32 v16, 0, v203
	v_add_f32_e32 v216, v202, v16
	ds_read_b128 v[202:205], v156 offset:17408
	ds_read_b128 v[206:209], v156 offset:17536
	v_mov_b32_e32 v16, v85
	v_pk_mul_f32 v[84:85], v[16:17], v[210:211]
	s_waitcnt lgkmcnt(1)
	v_lshlrev_b32_e32 v210, 16, v202
	v_add_f32_e32 v85, 0, v85
	v_add_f32_e32 v213, v84, v85
	s_waitcnt lgkmcnt(0)
	v_lshlrev_b32_e32 v211, 16, v206
	v_mov_b32_e32 v84, v10
	v_mov_b32_e32 v85, v18
	v_pk_mul_f32 v[210:211], v[84:85], v[210:211]
	v_mov_b32_e32 v18, v11
	v_add_f32_e32 v10, v218, v210
	v_add_f32_e32 v217, v10, v211
	v_and_b32_e32 v211, 0xffff0000, v206
	v_and_b32_e32 v210, 0xffff0000, v202
	v_pk_mul_f32 v[10:11], v[18:19], v[210:211]
	v_lshlrev_b32_e32 v211, 16, v203
	v_add_f32_e32 v10, v214, v10
	v_add_f32_e32 v206, v10, v11
	v_lshlrev_b32_e32 v210, 16, v207
	v_mov_b32_e32 v10, v20
	v_mov_b32_e32 v11, v12
	v_pk_mul_f32 v[210:211], v[10:11], v[210:211]
	v_and_b32_e32 v203, 0xffff0000, v203
	v_add_f32_e32 v12, v211, v219
	v_add_f32_e32 v210, v210, v12
	v_and_b32_e32 v202, 0xffff0000, v207
	v_mov_b32_e32 v12, v21
	v_pk_mul_f32 v[20:21], v[12:13], v[202:203]
	v_lshlrev_b32_e32 v203, 16, v208
	v_add_f32_e32 v21, v21, v215
	v_add_f32_e32 v207, v20, v21
	v_lshlrev_b32_e32 v202, 16, v204
	v_mov_b32_e32 v20, v6
	v_mov_b32_e32 v21, v78
	v_pk_mul_f32 v[202:203], v[20:21], v[202:203]
	s_nop 0
	v_add_f32_e32 v6, v220, v202
	v_add_f32_e32 v211, v6, v203
	v_and_b32_e32 v203, 0xffff0000, v204
	v_and_b32_e32 v202, 0xffff0000, v208
	v_mov_b32_e32 v6, v79
	v_pk_mul_f32 v[78:79], v[6:7], v[202:203]
	v_lshlrev_b32_e32 v203, 16, v205
	v_add_f32_e32 v79, v79, v212
	v_add_f32_e32 v204, v78, v79
	v_lshlrev_b32_e32 v202, 16, v209
	v_mov_b32_e32 v78, v80
	v_mov_b32_e32 v79, v8
	v_pk_mul_f32 v[202:203], v[78:79], v[202:203]
	s_nop 0
	v_add_f32_e32 v8, v203, v216
	v_add_f32_e32 v208, v202, v8
	v_mul_f32_e32 v8, 0xbfb8aa3b, v217
	v_and_b32_e32 v203, 0xffff0000, v205
	v_exp_f32_e32 v205, v8
	v_and_b32_e32 v202, 0xffff0000, v209
	v_mov_b32_e32 v8, v81
	v_pk_mul_f32 v[80:81], v[8:9], v[202:203]
	v_mul_f32_e32 v203, 0xbfb8aa3b, v206
	v_exp_f32_e32 v203, v203
	v_add_f32_e32 v81, v81, v213
	v_add_f32_e32 v202, 1.0, v205
	v_add_f32_e32 v205, v80, v81
	v_add_f32_e32 v80, 1.0, v203
	v_mul_f32_e32 v203, 0xbfb8aa3b, v207
	v_mul_f32_e32 v81, 0xbfb8aa3b, v210
	v_exp_f32_e32 v203, v203
	v_exp_f32_e32 v81, v81
	v_mul_f32_e32 v209, 0xbfb8aa3b, v211
	v_rcp_f32_e32 v80, v80
	v_add_f32_e32 v203, 1.0, v203
	v_exp_f32_e32 v209, v209
	v_add_f32_e32 v81, 1.0, v81
	v_rcp_f32_e32 v203, v203
	v_rcp_f32_e32 v81, v81
	v_mul_f32_e32 v206, v206, v80
	v_add_f32_e32 v80, 1.0, v209
	v_mul_f32_e32 v203, v207, v203
	v_rcp_f32_e32 v207, v80
	v_mul_f32_e32 v80, 0xbfb8aa3b, v204
	v_mul_f32_e32 v210, v210, v81
	v_exp_f32_e32 v209, v80
	v_mov_b32_e32 v80, v134
	v_mov_b32_e32 v81, v136
	v_pk_add_f32 v[80:81], v[80:81], 0 op_sel_hi:[1,0]
	v_mov_b32_e32 v136, v135
	v_pk_add_f32 v[80:81], v[80:81], v[136:137]
	v_mov_b32_e32 v136, v168
	v_mov_b32_e32 v137, v170
	v_pk_add_f32 v[136:137], v[136:137], 0 op_sel_hi:[1,0]
	v_mov_b32_e32 v170, v169
	v_mov_b32_e32 v134, v150
	v_mov_b32_e32 v135, v162
	v_mov_b32_e32 v162, v151
	v_pk_add_f32 v[136:137], v[136:137], v[170:171]
	v_mov_b32_e32 v150, v176
	v_mov_b32_e32 v151, v178
	v_pk_add_f32 v[80:81], v[80:81], v[134:135]
	v_pk_add_f32 v[136:137], v[136:137], v[150:151]
	v_mov_b32_e32 v178, v177
	v_pk_add_f32 v[80:81], v[80:81], v[162:163]
	v_pk_add_f32 v[136:137], v[136:137], v[178:179]
	v_mul_f32_e32 v134, 0xbfb8aa3b, v80
	v_mul_f32_e32 v135, 0xbfb8aa3b, v81
	v_mul_f32_e32 v150, 0xbfb8aa3b, v136
	v_mul_f32_e32 v151, 0xbfb8aa3b, v137
	v_exp_f32_e32 v134, v134
	v_exp_f32_e32 v135, v135
	v_exp_f32_e32 v150, v150
	v_exp_f32_e32 v151, v151
	v_add_f32_e32 v134, 1.0, v134
	v_add_f32_e32 v135, 1.0, v135
	v_add_f32_e32 v150, 1.0, v150
	v_add_f32_e32 v151, 1.0, v151
	v_rcp_f32_e32 v134, v134
	v_rcp_f32_e32 v135, v135
	v_rcp_f32_e32 v150, v150
	v_rcp_f32_e32 v151, v151
	v_add_f32_e32 v162, 1.0, v209
	v_pk_mul_f32 v[134:135], v[80:81], v[134:135]
	v_rcp_f32_e32 v168, v162
	v_pk_mul_f32 v[80:81], v[136:137], v[150:151]
; #define LAS __attribute__((address_space(3)))
; __device__ __forceinline__ float silu_acc(float x) { return x * frcp(1.0f + fexp(-x)); }
; __device__ __forceinline__ void gdn_unit(const Ctx& X, LAS unsigned char* hl, int b, int c, int h, int tid_h, int w4, int lane, int layer) {
;     ...
;                 for (int k = 0; k < 4; ++k) { float x8[8]; unpack8(*(const LAS u32x4*)(RAW + (tn * 67 + i + k) * 64 + cseg * 8), x8);
;                     y[tn][0] += wq[tn][k][0].x * x8[0]; y[tn][1] += wq[tn][k][0].y * x8[1]; y[tn][2] += wq[tn][k][0].z * x8[2]; y[tn][3] += wq[tn][k][0].w * x8[3];
;                     y[tn][4] += wq[tn][k][1].x * x8[4]; y[tn][5] += wq[tn][k][1].y * x8[5]; y[tn][6] += wq[tn][k][1].z * x8[6]; y[tn][7] += wq[tn][k][1].w * x8[7]; }
; #pragma unroll
;                 for (int e = 0; e < 8; ++e) y[tn][e] = silu_acc(y[tn][e]);
;             }
;             float sq = 0.f, sk = 0.f;
; #pragma unroll
;             for (int e = 0; e < 8; ++e) { sq += y[0][e] * y[0][e]; sk += y[1][e] * y[1][e]; }
;             sq += __shfl_xor(sq, 1); sq += __shfl_xor(sq, 2); sq += __shfl_xor(sq, 4);
;             sk += __shfl_xor(sk, 1); sk += __shfl_xor(sk, 2); sk += __shfl_xor(sk, 4);
	v_mov_b32_e32 v136, v121
	v_mov_b32_e32 v137, v119
	v_pk_add_f32 v[136:137], v[136:137], 0 op_sel_hi:[1,0]
	v_mov_b32_e32 v121, v118
	v_pk_add_f32 v[118:119], v[120:121], v[136:137]
	v_mov_b32_e32 v120, v143
	v_mov_b32_e32 v121, v139
	v_pk_add_f32 v[118:119], v[120:121], v[118:119]
	v_mov_b32_e32 v143, v138
	v_pk_add_f32 v[118:119], v[142:143], v[118:119]
	v_mov_b32_e32 v139, v149
	v_mul_f32_e32 v120, 0xbfb8aa3b, v119
	v_exp_f32_e32 v136, v120
	v_mul_f32_e32 v120, 0xbfb8aa3b, v118
	v_exp_f32_e32 v138, v120
	v_mov_b32_e32 v142, v175
	v_add_f32_e32 v136, 1.0, v136
	v_rcp_f32_e32 v137, v136
	v_add_f32_e32 v136, 1.0, v138
	v_mov_b32_e32 v138, v153
	v_pk_add_f32 v[138:139], v[138:139], 0 op_sel_hi:[1,0]
	v_mov_b32_e32 v153, v148
	v_pk_add_f32 v[138:139], v[152:153], v[138:139]
	v_mov_b32_e32 v143, v173
	v_pk_add_f32 v[138:139], v[142:143], v[138:139]
	v_mov_b32_e32 v175, v172
	v_pk_add_f32 v[138:139], v[174:175], v[138:139]
	v_rcp_f32_e32 v136, v136
	v_mul_f32_e32 v142, 0xbfb8aa3b, v139
	v_exp_f32_e32 v142, v142
	v_mul_f32_e32 v143, 0xbfb8aa3b, v138
	v_exp_f32_e32 v143, v143
	v_pk_mul_f32 v[118:119], v[118:119], v[136:137]
	v_add_f32_e32 v136, 1.0, v142
	v_rcp_f32_e32 v137, v136
	v_add_f32_e32 v136, 1.0, v143
	v_pk_mov_b32 v[142:143], v[112:113], v[110:111] op_sel:[1,0]
	v_mov_b32_e32 v113, v111
	v_pk_add_f32 v[142:143], v[142:143], 0 op_sel_hi:[1,0]
	v_rcp_f32_e32 v136, v136
	v_pk_add_f32 v[110:111], v[112:113], v[142:143]
	v_pk_mov_b32 v[112:113], v[126:127], v[122:123] op_sel:[1,0]
	v_mov_b32_e32 v127, v123
	v_pk_add_f32 v[110:111], v[112:113], v[110:111]
	v_mov_b32_e32 v143, v107
	v_pk_add_f32 v[112:113], v[126:127], v[110:111]
	v_pk_mul_f32 v[162:163], v[134:135], v[134:135]
	v_mul_f32_e32 v110, 0xbfb8aa3b, v113
	v_exp_f32_e32 v110, v110
	v_mul_f32_e32 v111, 0xbfb8aa3b, v112
	v_exp_f32_e32 v111, v111
	v_pk_mul_f32 v[120:121], v[80:81], v[80:81]
	v_add_f32_e32 v110, 1.0, v110
	v_rcp_f32_e32 v123, v110
	v_add_f32_e32 v110, 1.0, v111
	v_rcp_f32_e32 v122, v110
	v_pk_mul_f32 v[110:111], v[138:139], v[136:137]
	v_pk_mov_b32 v[138:139], v[166:167], v[164:165] op_sel:[1,0]
	v_mov_b32_e32 v167, v165
	v_pk_mul_f32 v[112:113], v[112:113], v[122:123]
	v_pk_mov_b32 v[122:123], v[144:145], v[140:141] op_sel:[1,0]
	v_mov_b32_e32 v145, v141
	v_pk_add_f32 v[122:123], v[122:123], 0 op_sel_hi:[1,0]
	v_pk_mul_f32 v[126:127], v[118:119], v[118:119]
	v_pk_add_f32 v[122:123], v[144:145], v[122:123]
	v_pk_mul_f32 v[136:137], v[110:111], v[110:111]
	v_pk_add_f32 v[122:123], v[138:139], v[122:123]
	v_rcp_f32_e32 v202, v202
	v_pk_add_f32 v[122:123], v[166:167], v[122:123]
	v_mul_f32_e32 v202, v217, v202
	v_mul_f32_e32 v138, 0xbfb8aa3b, v123
	v_exp_f32_e32 v140, v138
	v_mul_f32_e32 v138, 0xbfb8aa3b, v122
	v_exp_f32_e32 v142, v138
	v_pk_mul_f32 v[138:139], v[112:113], v[112:113]
	v_add_f32_e32 v140, 1.0, v140
	v_rcp_f32_e32 v141, v140
	v_add_f32_e32 v140, 1.0, v142
	v_mov_b32_e32 v142, v109
	v_pk_add_f32 v[142:143], v[142:143], 0 op_sel_hi:[1,0]
	v_mov_b32_e32 v109, v106
	v_pk_add_f32 v[106:107], v[108:109], v[142:143]
	v_mov_b32_e32 v108, v117
	v_mov_b32_e32 v109, v115
	v_pk_add_f32 v[106:107], v[108:109], v[106:107]
	v_mov_b32_e32 v117, v114
	v_pk_add_f32 v[106:107], v[116:117], v[106:107]
	v_rcp_f32_e32 v140, v140
	v_mul_f32_e32 v108, 0xbfb8aa3b, v107
	v_exp_f32_e32 v108, v108
	v_mul_f32_e32 v109, 0xbfb8aa3b, v106
	v_exp_f32_e32 v114, v109
	v_mov_b32_e32 v115, v125
	v_add_f32_e32 v108, 1.0, v108
	v_rcp_f32_e32 v109, v108
	v_add_f32_e32 v108, 1.0, v114
	v_mov_b32_e32 v114, v129
	v_pk_add_f32 v[114:115], v[114:115], 0 op_sel_hi:[1,0]
	v_mov_b32_e32 v129, v124
	v_pk_mul_f32 v[116:117], v[122:123], v[140:141]
	v_pk_add_f32 v[114:115], v[128:129], v[114:115]
	v_mov_b32_e32 v122, v89
	v_mov_b32_e32 v123, v147
	v_pk_add_f32 v[114:115], v[122:123], v[114:115]
	v_mov_b32_e32 v89, v146
	v_pk_add_f32 v[88:89], v[88:89], v[114:115]
	v_rcp_f32_e32 v108, v108
	v_mul_f32_e32 v114, 0xbfb8aa3b, v89
	v_exp_f32_e32 v114, v114
	v_mul_f32_e32 v115, 0xbfb8aa3b, v88
	v_exp_f32_e32 v122, v115
	v_mov_b32_e32 v124, v120
	v_add_f32_e32 v114, 1.0, v114
	v_rcp_f32_e32 v115, v114
	v_add_f32_e32 v114, 1.0, v122
	v_rcp_f32_e32 v114, v114
	v_mov_b32_e32 v125, v162
	v_mov_b32_e32 v162, v121
	v_pk_add_f32 v[120:121], v[124:125], v[162:163]
	v_mov_b32_e32 v124, v137
	v_mov_b32_e32 v125, v127
	v_pk_mul_f32 v[122:123], v[116:117], v[116:117]
	v_pk_add_f32 v[120:121], v[124:125], v[120:121]
	v_mov_b32_e32 v137, v126
	v_pk_mul_f32 v[106:107], v[106:107], v[108:109]
	v_pk_mul_f32 v[88:89], v[88:89], v[114:115]
	v_pk_add_f32 v[120:121], v[136:137], v[120:121]
	v_mov_b32_e32 v124, v123
	v_mov_b32_e32 v125, v139
	v_pk_mul_f32 v[108:109], v[106:107], v[106:107]
	v_pk_mul_f32 v[114:115], v[88:89], v[88:89]
	v_pk_add_f32 v[120:121], v[124:125], v[120:121]
	v_mov_b32_e32 v123, v138
	v_pk_add_f32 v[120:121], v[122:123], v[120:121]
	v_mov_b32_e32 v122, v115
	v_mov_b32_e32 v123, v109
	v_pk_add_f32 v[120:121], v[122:123], v[120:121]
	v_mov_b32_e32 v115, v108
	v_pk_add_f32 v[108:109], v[114:115], v[120:121]
	ds_bpermute_b32 v115, v197, v109
	ds_bpermute_b32 v114, v197, v108
	v_mul_f32_e32 v120, 0xbfb8aa3b, v208
	v_mul_f32_e32 v121, 0xbfb8aa3b, v205
	v_exp_f32_e32 v120, v120
	v_exp_f32_e32 v121, v121
	s_waitcnt lgkmcnt(0)
	v_pk_add_f32 v[108:109], v[108:109], v[114:115]
	ds_bpermute_b32 v115, v196, v109
	ds_bpermute_b32 v114, v196, v108
	v_add_f32_e32 v120, 1.0, v120
	v_add_f32_e32 v121, 1.0, v121
	v_rcp_f32_e32 v120, v120
	v_rcp_f32_e32 v121, v121
	s_waitcnt lgkmcnt(0)
	v_pk_add_f32 v[108:109], v[108:109], v[114:115]
	ds_bpermute_b32 v115, v195, v109
	ds_bpermute_b32 v114, v195, v108
	v_mul_f32_e32 v122, v211, v207
	v_mul_f32_e32 v123, v204, v168
	v_mul_f32_e32 v120, v208, v120
	v_mul_f32_e32 v121, v205, v121
	s_waitcnt lgkmcnt(0)
; #define LAS __attribute__((address_space(3)))
; __device__ __forceinline__ bf16_t f2bf(float f) { return (bf16_t)(pk2(f, 0.f) & 0xffffu); }
; __device__ __forceinline__ float fexp(float x) { return __expf(x); }
; __device__ __forceinline__ void gdn_unit(const Ctx& X, LAS unsigned char* hl, int b, int c, int h, int tid_h, int w4, int lane, int layer) {
;     ...
;         for (int rs = 0; rs < 2; ++rs) {
;             const int i = i0 + 32 * rs;
;             const float bi = Bs[i], Gi = Gs[i];
;             float y[3][8];
; #pragma unroll
;             for (int tn = 0; tn < 3; ++tn) {
; #pragma unroll
;                 for (int e = 0; e < 8; ++e) y[tn][e] = 0.f;
; #pragma unroll
;                 for (int k = 0; k < 4; ++k) { float x8[8]; unpack8(*(const LAS u32x4*)(RAW + (tn * 67 + i + k) * 64 + cseg * 8), x8);
;                     y[tn][0] += wq[tn][k][0].x * x8[0]; y[tn][1] += wq[tn][k][0].y * x8[1]; y[tn][2] += wq[tn][k][0].z * x8[2]; y[tn][3] += wq[tn][k][0].w * x8[3];
;                     y[tn][4] += wq[tn][k][1].x * x8[4]; y[tn][5] += wq[tn][k][1].y * x8[5]; y[tn][6] += wq[tn][k][1].z * x8[6]; y[tn][7] += wq[tn][k][1].w * x8[7]; }
;     ...
;             float sq = 0.f, sk = 0.f;
; #pragma unroll
;             for (int e = 0; e < 8; ++e) { sq += y[0][e] * y[0][e]; sk += y[1][e] * y[1][e]; }
;             sq += __shfl_xor(sq, 1); sq += __shfl_xor(sq, 2); sq += __shfl_xor(sq, 4);
;             sk += __shfl_xor(sk, 1); sk += __shfl_xor(sk, 2); sk += __shfl_xor(sk, 4);
;             const float rq = 0.125f * rsqrtf(sq + 1e-6f), rk = rsqrtf(sk + 1e-6f), kd = rk * fexp(G63 - Gi);
;             float t8[8];
; #pragma unroll
;             for (int e = 0; e < 8; ++e) t8[e] = y[0][e] * rq;
;             *(LAS u32x4*)(Q + i * LT + cseg * 8) = pack8(t8);
; #pragma unroll
;             for (int e = 0; e < 8; ++e) t8[e] = y[1][e] * rk;
;             *(LAS u32x4*)(K + i * LT + cseg * 8) = pack8(t8);
; #pragma unroll
;             for (int e = 0; e < 8; ++e) t8[e] = y[1][e] * rk * bi;
;             *(LAS u32x4*)(KB + i * LT + cseg * 8) = pack8(t8);
;             *(LAS u32x4*)(V + i * LT + cseg * 8) = pack8(y[2]);
; #pragma unroll
;             for (int e = 0; e < 8; ++e) KDT[(cseg * 8 + e) * LT + i] = f2bf(y[1][e] * kd);
	v_pk_add_f32 v[108:109], v[108:109], v[114:115]
	v_sub_f32_e32 v115, v194, v201
	v_pk_add_f32 v[108:109], v[108:109], s[4:5] op_sel_hi:[1,0]
	v_mul_f32_e32 v115, 0x3fb8aa3b, v115
	v_mul_f32_e32 v114, 0x4b800000, v109
	v_cmp_gt_f32_e32 vcc, s3, v109
	v_cmp_gt_f32_e64 s[0:1], s3, v108
	v_exp_f32_e32 v124, v115
	v_cndmask_b32_e32 v109, v109, v114, vcc
	v_rsq_f32_e32 v109, v109
	v_mul_f32_e32 v114, 0x4b800000, v108
	v_cndmask_b32_e64 v108, v108, v114, s[0:1]
	v_rsq_f32_e32 v108, v108
	v_mul_f32_e32 v114, 0x45800000, v109
	v_cndmask_b32_e32 v109, v109, v114, vcc
	v_mul_f32_e32 v109, 0x3e000000, v109
	v_mul_f32_e32 v114, 0x45800000, v108
	v_mul_f32_e32 v115, v134, v109
	v_mul_f32_e32 v125, v135, v109
	v_mul_f32_e32 v119, v119, v109
	v_mul_f32_e32 v118, v118, v109
	v_mul_f32_e32 v126, v113, v109
	v_mul_f32_e32 v127, v112, v109
	v_mul_f32_e32 v107, v107, v109
	v_mul_f32_e32 v106, v106, v109
	v_cndmask_b32_e64 v109, v108, v114, s[0:1]
	v_mul_lo_u32 v108, v191, s44
	v_cvt_pk_bf16_f32 v112, v115, v125
	v_cvt_pk_bf16_f32 v113, v119, v118
	v_cvt_pk_bf16_f32 v114, v126, v127
	v_cvt_pk_bf16_f32 v115, v107, v106
	v_add_u32_e32 v106, v193, v108
	ds_write_b128 v106, v[112:115]
	v_mul_f32_e32 v106, v80, v109
	v_mul_f32_e32 v107, v81, v109
	v_mul_f32_e32 v118, v111, v109
	v_mul_f32_e32 v119, v110, v109
	v_mul_f32_e32 v125, v117, v109
	v_mul_f32_e32 v126, v116, v109
	v_mul_f32_e32 v127, v89, v109
	v_mul_f32_e32 v128, v88, v109
	v_cvt_pk_bf16_f32 v112, v106, v107
	v_cvt_pk_bf16_f32 v113, v118, v119
	v_cvt_pk_bf16_f32 v114, v125, v126
	v_cvt_pk_bf16_f32 v115, v127, v128
	v_add_u32_e32 v129, v192, v108
	v_mul_f32_e32 v106, v200, v106
	ds_write_b128 v129, v[112:115]
	v_mul_f32_e32 v107, v200, v107
	v_mul_f32_e32 v113, v200, v118
	v_mul_f32_e32 v114, v200, v119
	v_mul_f32_e32 v115, v200, v125
	v_cvt_pk_bf16_f32 v112, v106, v107
	v_add_u32_e32 v106, v155, v108
	v_mul_f32_e32 v118, v200, v126
	v_mul_f32_e32 v119, v200, v127
	v_mul_f32_e32 v125, v200, v128
	v_mul_f32_e32 v109, v124, v109
	v_cvt_pk_bf16_f32 v113, v113, v114
	v_cvt_pk_bf16_f32 v114, v115, v118
	v_cvt_pk_bf16_f32 v115, v119, v125
	ds_write_b128 v106, v[112:115]
	v_add_u32_e32 v106, v133, v108
	v_cvt_pk_bf16_f32 v112, v202, v206
	v_cvt_pk_bf16_f32 v113, v210, v203
	v_cvt_pk_bf16_f32 v114, v122, v123
	v_cvt_pk_bf16_f32 v115, v120, v121
	ds_write_b128 v106, v[112:115]
	v_lshlrev_b32_e32 v106, 1, v191
	v_mul_f32_e32 v80, v80, v109
	v_mul_u32_u24_e32 v107, 0x90, v190
	v_cvt_pk_bf16_f32 v80, v80, v157
	v_add3_u32 v107, v131, v106, v107
	ds_write_b16 v107, v80
	v_mul_f32_e32 v80, v81, v109
	v_cvt_pk_bf16_f32 v80, v80, v157
	ds_write_b16 v107, v80 offset:144
	v_mul_f32_e32 v80, v111, v109
	v_cvt_pk_bf16_f32 v80, v80, v157
	ds_write_b16 v107, v80 offset:288
	v_mul_f32_e32 v80, v110, v109
	v_cvt_pk_bf16_f32 v80, v80, v157
	ds_write_b16 v107, v80 offset:432
	v_mul_f32_e32 v80, v117, v109
	v_cvt_pk_bf16_f32 v80, v80, v157
	ds_write_b16 v107, v80 offset:576
	v_mul_f32_e32 v80, v116, v109
	v_cvt_pk_bf16_f32 v80, v80, v157
	ds_write_b16 v107, v80 offset:720
	v_mul_f32_e32 v80, v89, v109
	v_cvt_pk_bf16_f32 v80, v80, v157
	ds_write_b16 v107, v80 offset:864
	v_mul_f32_e32 v80, v88, v109
	v_cvt_pk_bf16_f32 v80, v80, v157
	ds_write_b16 v107, v80 offset:1008
	ds_read_b128 v[112:115], v156 offset:4224
	ds_read_b128 v[116:119], v156 offset:4096
	ds_read_b32 v109, v198 offset:128
	ds_read_b32 v110, v199 offset:128
	ds_read_b128 v[120:123], v156 offset:4352
	ds_read_b128 v[124:127], v156 offset:4480
	v_and_b32_e32 v106, 15, v130
	s_waitcnt lgkmcnt(5)
	v_lshlrev_b32_e32 v81, 16, v112
	s_waitcnt lgkmcnt(4)
	v_lshlrev_b32_e32 v80, 16, v116
	v_pk_mul_f32 v[88:89], v[102:103], v[80:81]
	v_and_b32_e32 v81, 0xffff0000, v112
	v_and_b32_e32 v80, 0xffff0000, v116
	v_pk_mul_f32 v[102:103], v[74:75], v[80:81]
	v_lshlrev_b32_e32 v75, 16, v117
	v_lshlrev_b32_e32 v74, 16, v113
	v_pk_mul_f32 v[74:75], v[66:67], v[74:75]
	v_and_b32_e32 v67, 0xffff0000, v117
	v_and_b32_e32 v66, 0xffff0000, v113
	v_pk_mul_f32 v[80:81], v[68:69], v[66:67]
	v_and_b32_e32 v69, 0xffff0000, v118
	v_and_b32_e32 v68, 0xffff0000, v114
	v_pk_mul_f32 v[68:69], v[58:59], v[68:69]
	v_lshlrev_b32_e32 v59, 16, v119
	v_lshlrev_b32_e32 v58, 16, v115
	v_pk_mul_f32 v[58:59], v[76:77], v[58:59]
	v_and_b32_e32 v77, 0xffff0000, v119
	v_and_b32_e32 v76, 0xffff0000, v115
	v_pk_mul_f32 v[60:61], v[60:61], v[76:77]
	s_waitcnt lgkmcnt(0)
	v_lshlrev_b32_e32 v77, 16, v124
	v_lshlrev_b32_e32 v76, 16, v120
	v_lshlrev_b32_e32 v67, 16, v114
	v_lshlrev_b32_e32 v66, 16, v118
	v_pk_mul_f32 v[98:99], v[98:99], v[76:77]
	v_and_b32_e32 v77, 0xffff0000, v124
	v_and_b32_e32 v76, 0xffff0000, v120
	v_pk_mul_f32 v[66:67], v[104:105], v[66:67]
	v_pk_mul_f32 v[104:105], v[70:71], v[76:77]
	v_lshlrev_b32_e32 v71, 16, v121
	v_lshlrev_b32_e32 v70, 16, v125
	ds_read_b128 v[112:115], v156 offset:12672
	ds_read_b128 v[116:119], v156 offset:12800
	v_pk_mul_f32 v[70:71], v[62:63], v[70:71]
	v_and_b32_e32 v63, 0xffff0000, v121
	v_and_b32_e32 v62, 0xffff0000, v125
	v_pk_mul_f32 v[76:77], v[64:65], v[62:63]
	v_and_b32_e32 v65, 0xffff0000, v122
	v_and_b32_e32 v64, 0xffff0000, v126
	v_pk_mul_f32 v[64:65], v[54:55], v[64:65]
	v_lshlrev_b32_e32 v55, 16, v123
	v_lshlrev_b32_e32 v54, 16, v127
	v_pk_mul_f32 v[54:55], v[72:73], v[54:55]
	v_and_b32_e32 v73, 0xffff0000, v123
	v_and_b32_e32 v72, 0xffff0000, v127
	v_pk_mul_f32 v[56:57], v[56:57], v[72:73]
	s_waitcnt lgkmcnt(0)
; #define LAS __attribute__((address_space(3)))
; __device__ __forceinline__ float silu_acc(float x) { return x * frcp(1.0f + fexp(-x)); }
; __device__ __forceinline__ void gdn_unit(const Ctx& X, LAS unsigned char* hl, int b, int c, int h, int tid_h, int w4, int lane, int layer) {
;     ...
;             for (int tn = 0; tn < 3; ++tn) {
; #pragma unroll
;                 for (int e = 0; e < 8; ++e) y[tn][e] = 0.f;
; #pragma unroll
;                 for (int k = 0; k < 4; ++k) { float x8[8]; unpack8(*(const LAS u32x4*)(RAW + (tn * 67 + i + k) * 64 + cseg * 8), x8);
;                     y[tn][0] += wq[tn][k][0].x * x8[0]; y[tn][1] += wq[tn][k][0].y * x8[1]; y[tn][2] += wq[tn][k][0].z * x8[2]; y[tn][3] += wq[tn][k][0].w * x8[3];
;                     y[tn][4] += wq[tn][k][1].x * x8[4]; y[tn][5] += wq[tn][k][1].y * x8[5]; y[tn][6] += wq[tn][k][1].z * x8[6]; y[tn][7] += wq[tn][k][1].w * x8[7]; }
; #pragma unroll
;                 for (int e = 0; e < 8; ++e) y[tn][e] = silu_acc(y[tn][e]);
;             }
	v_lshlrev_b32_e32 v73, 16, v116
	v_lshlrev_b32_e32 v72, 16, v112
	v_lshlrev_b32_e32 v63, 16, v126
	v_lshlrev_b32_e32 v62, 16, v122
	v_pk_mul_f32 v[94:95], v[94:95], v[72:73]
	v_and_b32_e32 v73, 0xffff0000, v116
	v_and_b32_e32 v72, 0xffff0000, v112
	v_pk_mul_f32 v[62:63], v[100:101], v[62:63]
	v_pk_mul_f32 v[100:101], v[50:51], v[72:73]
	v_lshlrev_b32_e32 v51, 16, v113
	v_lshlrev_b32_e32 v50, 16, v117
	ds_read_b128 v[120:123], v156 offset:12928
	ds_read_b128 v[124:127], v156 offset:13056
	v_pk_mul_f32 v[50:51], v[46:47], v[50:51]
	v_and_b32_e32 v47, 0xffff0000, v113
	v_and_b32_e32 v46, 0xffff0000, v117
	v_pk_mul_f32 v[72:73], v[48:49], v[46:47]
	v_and_b32_e32 v49, 0xffff0000, v114
	v_and_b32_e32 v48, 0xffff0000, v118
	v_pk_mul_f32 v[48:49], v[38:39], v[48:49]
	v_lshlrev_b32_e32 v39, 16, v115
	v_lshlrev_b32_e32 v38, 16, v119
	v_pk_mul_f32 v[38:39], v[52:53], v[38:39]
	v_and_b32_e32 v53, 0xffff0000, v115
	v_and_b32_e32 v52, 0xffff0000, v119
	v_pk_mul_f32 v[40:41], v[40:41], v[52:53]
	s_waitcnt lgkmcnt(0)
	v_lshlrev_b32_e32 v53, 16, v124
	v_lshlrev_b32_e32 v52, 16, v120
	v_lshlrev_b32_e32 v47, 16, v118
	v_lshlrev_b32_e32 v46, 16, v114
	v_pk_mul_f32 v[90:91], v[90:91], v[52:53]
	v_and_b32_e32 v53, 0xffff0000, v124
	v_and_b32_e32 v52, 0xffff0000, v120
	v_pk_mul_f32 v[46:47], v[96:97], v[46:47]
	v_pk_mul_f32 v[96:97], v[42:43], v[52:53]
	v_lshlrev_b32_e32 v43, 16, v121
	v_lshlrev_b32_e32 v42, 16, v125
	ds_read_b128 v[112:115], v156 offset:21248
	ds_read_b128 v[116:119], v156 offset:21376
	v_pk_mul_f32 v[42:43], v[34:35], v[42:43]
	v_and_b32_e32 v35, 0xffff0000, v121
	v_and_b32_e32 v34, 0xffff0000, v125
	v_pk_mul_f32 v[52:53], v[36:37], v[34:35]
	v_and_b32_e32 v37, 0xffff0000, v122
	v_and_b32_e32 v36, 0xffff0000, v126
	v_pk_mul_f32 v[36:37], v[30:31], v[36:37]
	v_lshlrev_b32_e32 v31, 16, v123
	v_lshlrev_b32_e32 v30, 16, v127
	v_pk_mul_f32 v[30:31], v[44:45], v[30:31]
	v_and_b32_e32 v45, 0xffff0000, v123
	v_and_b32_e32 v44, 0xffff0000, v127
	v_pk_mul_f32 v[32:33], v[32:33], v[44:45]
	s_waitcnt lgkmcnt(0)
	v_lshlrev_b32_e32 v45, 16, v116
	v_lshlrev_b32_e32 v44, 16, v112
	v_pk_mul_f32 v[44:45], v[86:87], v[44:45]
	v_lshlrev_b32_e32 v35, 16, v126
	v_add_f32_e32 v44, 0, v44
	v_add_f32_e32 v86, v44, v45
	v_and_b32_e32 v45, 0xffff0000, v116
	v_and_b32_e32 v44, 0xffff0000, v112
	v_pk_mul_f32 v[26:27], v[26:27], v[44:45]
	v_lshlrev_b32_e32 v34, 16, v122
	v_add_f32_e32 v26, 0, v26
	v_add_f32_e32 v44, v26, v27
	v_lshlrev_b32_e32 v27, 16, v113
	v_lshlrev_b32_e32 v26, 16, v117
	v_pk_mul_f32 v[22:23], v[22:23], v[26:27]
	v_pk_mul_f32 v[34:35], v[92:93], v[34:35]
	v_add_f32_e32 v23, 0, v23
	v_add_f32_e32 v45, v22, v23
	v_and_b32_e32 v23, 0xffff0000, v113
	v_and_b32_e32 v22, 0xffff0000, v117
	v_pk_mul_f32 v[22:23], v[24:25], v[22:23]
	s_nop 0
	v_add_f32_e32 v23, 0, v23
	v_add_f32_e32 v87, v22, v23
	v_lshlrev_b32_e32 v23, 16, v118
	v_lshlrev_b32_e32 v22, 16, v114
	v_pk_mul_f32 v[22:23], v[28:29], v[22:23]
	s_nop 0
	v_add_f32_e32 v22, 0, v22
	v_add_f32_e32 v92, v22, v23
	v_and_b32_e32 v23, 0xffff0000, v114
	v_and_b32_e32 v22, 0xffff0000, v118
	v_pk_mul_f32 v[14:15], v[14:15], v[22:23]
	ds_read_b128 v[22:25], v156 offset:21504
	ds_read_b128 v[26:29], v156 offset:21632
	v_add_f32_e32 v15, 0, v15
	v_add_f32_e32 v93, v14, v15
	v_lshlrev_b32_e32 v15, 16, v115
	v_lshlrev_b32_e32 v14, 16, v119
	v_pk_mul_f32 v[14:15], v[82:83], v[14:15]
	s_nop 0
	v_add_f32_e32 v15, 0, v15
	v_add_f32_e32 v82, v14, v15
	v_and_b32_e32 v15, 0xffff0000, v115
	v_and_b32_e32 v14, 0xffff0000, v119
	v_pk_mul_f32 v[14:15], v[16:17], v[14:15]
	s_nop 0
	v_add_f32_e32 v15, 0, v15
	v_add_f32_e32 v16, v14, v15
	s_waitcnt lgkmcnt(0)
	v_lshlrev_b32_e32 v15, 16, v26
	v_lshlrev_b32_e32 v14, 16, v22
	v_pk_mul_f32 v[14:15], v[84:85], v[14:15]
	s_nop 0
	v_add_f32_e32 v14, v86, v14
	v_add_f32_e32 v17, v14, v15
	v_and_b32_e32 v15, 0xffff0000, v26
	v_and_b32_e32 v14, 0xffff0000, v22
	v_pk_mul_f32 v[14:15], v[18:19], v[14:15]
	v_mov_b32_e32 v19, v51
	v_add_f32_e32 v14, v44, v14
	v_add_f32_e32 v18, v14, v15
	v_lshlrev_b32_e32 v15, 16, v23
	v_lshlrev_b32_e32 v14, 16, v27
	v_pk_mul_f32 v[10:11], v[10:11], v[14:15]
	s_nop 0
	v_add_f32_e32 v11, v11, v45
	v_add_f32_e32 v14, v10, v11
	v_and_b32_e32 v11, 0xffff0000, v23
	v_and_b32_e32 v10, 0xffff0000, v27
	v_pk_mul_f32 v[10:11], v[12:13], v[10:11]
	v_mov_b32_e32 v13, v96
	v_add_f32_e32 v11, v11, v87
	v_add_f32_e32 v12, v10, v11
	v_lshlrev_b32_e32 v11, 16, v28
	v_lshlrev_b32_e32 v10, 16, v24
	v_pk_mul_f32 v[10:11], v[20:21], v[10:11]
	v_mov_b32_e32 v96, v91
	v_add_f32_e32 v10, v92, v10
	v_add_f32_e32 v44, v10, v11
	v_and_b32_e32 v11, 0xffff0000, v24
	v_and_b32_e32 v10, 0xffff0000, v28
	v_pk_mul_f32 v[6:7], v[6:7], v[10:11]
	v_mov_b32_e32 v11, v100
	v_add_f32_e32 v7, v7, v93
	v_add_f32_e32 v45, v6, v7
	v_lshlrev_b32_e32 v7, 16, v25
	v_lshlrev_b32_e32 v6, 16, v29
	v_pk_mul_f32 v[6:7], v[78:79], v[6:7]
	v_mov_b32_e32 v100, v95
	v_add_f32_e32 v7, v7, v82
	v_add_f32_e32 v78, v6, v7
	v_mul_f32_e32 v6, 0xbfb8aa3b, v17
	v_exp_f32_e32 v10, v6
	v_and_b32_e32 v7, 0xffff0000, v25
	v_and_b32_e32 v6, 0xffff0000, v29
	v_pk_mul_f32 v[6:7], v[8:9], v[6:7]
	v_mul_f32_e32 v9, 0xbfb8aa3b, v18
	v_exp_f32_e32 v9, v9
	v_add_f32_e32 v8, 1.0, v10
	v_rcp_f32_e32 v8, v8
	v_add_f32_e32 v7, v7, v16
	v_add_f32_e32 v79, v6, v7
	v_add_f32_e32 v6, 1.0, v9
	v_mul_f32_e32 v9, 0xbfb8aa3b, v44
	v_mul_f32_e32 v7, 0xbfb8aa3b, v14
	v_rcp_f32_e32 v6, v6
	v_exp_f32_e32 v9, v9
	v_exp_f32_e32 v7, v7
	v_mul_f32_e32 v82, v17, v8
	v_mul_f32_e32 v8, 0xbfb8aa3b, v12
	v_exp_f32_e32 v8, v8
	v_mul_f32_e32 v83, v18, v6
	v_add_f32_e32 v6, 1.0, v9
	v_add_f32_e32 v7, 1.0, v7
	v_rcp_f32_e32 v86, v6
	v_mul_f32_e32 v6, 0xbfb8aa3b, v45
; __device__ __forceinline__ float silu_acc(float x) { return x * frcp(1.0f + fexp(-x)); }
; __device__ __forceinline__ void gdn_unit(const Ctx& X, LAS unsigned char* hl, int b, int c, int h, int tid_h, int w4, int lane, int layer) {
;     ...
;                 for (int e = 0; e < 8; ++e) y[tn][e] = silu_acc(y[tn][e]);
;             }
;             float sq = 0.f, sk = 0.f;
; #pragma unroll
;             for (int e = 0; e < 8; ++e) { sq += y[0][e] * y[0][e]; sk += y[1][e] * y[1][e]; }
;             sq += __shfl_xor(sq, 1); sq += __shfl_xor(sq, 2); sq += __shfl_xor(sq, 4);
;             sk += __shfl_xor(sk, 1); sk += __shfl_xor(sk, 2); sk += __shfl_xor(sk, 4);
	v_rcp_f32_e32 v7, v7
	v_exp_f32_e32 v10, v6
	v_add_f32_e32 v8, 1.0, v8
	v_rcp_f32_e32 v8, v8
	v_mul_f32_e32 v84, v14, v7
	v_mov_b32_e32 v6, v88
	v_mov_b32_e32 v7, v102
	v_add_f32_e32 v14, 1.0, v10
	v_mov_b32_e32 v10, v94
	v_pk_add_f32 v[6:7], v[6:7], 0 op_sel_hi:[1,0]
	v_mov_b32_e32 v102, v89
	v_pk_add_f32 v[10:11], v[10:11], 0 op_sel_hi:[1,0]
	v_mul_f32_e32 v85, v12, v8
	v_pk_add_f32 v[6:7], v[6:7], v[102:103]
	v_mov_b32_e32 v8, v98
	v_mov_b32_e32 v9, v104
	v_pk_add_f32 v[10:11], v[10:11], v[100:101]
	v_mov_b32_e32 v12, v90
	v_pk_add_f32 v[6:7], v[6:7], v[8:9]
	v_mov_b32_e32 v104, v99
	v_pk_add_f32 v[10:11], v[10:11], v[12:13]
	v_pk_add_f32 v[6:7], v[6:7], v[104:105]
	v_pk_add_f32 v[10:11], v[10:11], v[96:97]
	v_mul_f32_e32 v8, 0xbfb8aa3b, v6
	v_mul_f32_e32 v9, 0xbfb8aa3b, v7
	v_mul_f32_e32 v12, 0xbfb8aa3b, v10
	v_mul_f32_e32 v13, 0xbfb8aa3b, v11
	v_exp_f32_e32 v8, v8
	v_exp_f32_e32 v9, v9
	v_exp_f32_e32 v12, v12
	v_exp_f32_e32 v13, v13
	v_add_f32_e32 v8, 1.0, v8
	v_add_f32_e32 v9, 1.0, v9
	v_add_f32_e32 v12, 1.0, v12
	v_add_f32_e32 v13, 1.0, v13
	v_rcp_f32_e32 v8, v8
	v_rcp_f32_e32 v9, v9
	v_rcp_f32_e32 v12, v12
	v_rcp_f32_e32 v13, v13
	v_mov_b32_e32 v20, v53
	v_pk_mul_f32 v[8:9], v[6:7], v[8:9]
	v_mov_b32_e32 v21, v43
	v_pk_mul_f32 v[6:7], v[10:11], v[12:13]
	v_mov_b32_e32 v10, v81
	v_mov_b32_e32 v11, v75
	v_pk_add_f32 v[10:11], v[10:11], 0 op_sel_hi:[1,0]
	v_mov_b32_e32 v81, v74
	v_pk_add_f32 v[10:11], v[80:81], v[10:11]
	v_mov_b32_e32 v12, v77
	v_mov_b32_e32 v13, v71
	v_pk_add_f32 v[10:11], v[12:13], v[10:11]
	v_mov_b32_e32 v77, v70
	v_pk_add_f32 v[10:11], v[76:77], v[10:11]
	v_mov_b32_e32 v53, v42
	v_mul_f32_e32 v12, 0xbfb8aa3b, v11
	v_exp_f32_e32 v16, v12
	v_mul_f32_e32 v12, 0xbfb8aa3b, v10
	v_exp_f32_e32 v18, v12
	v_pk_mov_b32 v[22:23], v[64:65], v[62:63] op_sel:[1,0]
	v_add_f32_e32 v16, 1.0, v16
	v_rcp_f32_e32 v17, v16
	v_add_f32_e32 v16, 1.0, v18
	v_mov_b32_e32 v18, v73
	v_pk_add_f32 v[18:19], v[18:19], 0 op_sel_hi:[1,0]
	v_mov_b32_e32 v73, v50
	v_pk_add_f32 v[18:19], v[72:73], v[18:19]
	v_rcp_f32_e32 v16, v16
	v_pk_add_f32 v[18:19], v[20:21], v[18:19]
	v_mov_b32_e32 v65, v63
	v_pk_add_f32 v[18:19], v[52:53], v[18:19]
	v_pk_mul_f32 v[10:11], v[10:11], v[16:17]
	v_mul_f32_e32 v20, 0xbfb8aa3b, v19
	v_exp_f32_e32 v20, v20
	v_mul_f32_e32 v21, 0xbfb8aa3b, v18
	v_exp_f32_e32 v21, v21
	v_pk_mov_b32 v[26:27], v[36:37], v[34:35] op_sel:[1,0]
	v_add_f32_e32 v16, 1.0, v20
	v_rcp_f32_e32 v17, v16
	v_add_f32_e32 v16, 1.0, v21
	v_pk_mov_b32 v[20:21], v[68:69], v[66:67] op_sel:[1,0]
	v_mov_b32_e32 v69, v67
	v_pk_add_f32 v[20:21], v[20:21], 0 op_sel_hi:[1,0]
	v_mov_b32_e32 v37, v35
	v_pk_add_f32 v[20:21], v[68:69], v[20:21]
	v_mov_b32_e32 v35, v59
	v_pk_add_f32 v[20:21], v[22:23], v[20:21]
	v_rcp_f32_e32 v16, v16
	v_pk_add_f32 v[20:21], v[64:65], v[20:21]
	v_rcp_f32_e32 v87, v14
	v_mul_f32_e32 v22, 0xbfb8aa3b, v21
	v_exp_f32_e32 v22, v22
	v_mul_f32_e32 v23, 0xbfb8aa3b, v20
	v_exp_f32_e32 v24, v23
	v_pk_mul_f32 v[14:15], v[8:9], v[8:9]
	v_add_f32_e32 v22, 1.0, v22
	v_rcp_f32_e32 v23, v22
	v_add_f32_e32 v22, 1.0, v24
	v_rcp_f32_e32 v22, v22
	v_pk_mul_f32 v[12:13], v[6:7], v[6:7]
	v_pk_mul_f32 v[16:17], v[18:19], v[16:17]
	v_pk_mul_f32 v[24:25], v[10:11], v[10:11]
	v_pk_mul_f32 v[20:21], v[20:21], v[22:23]
	v_pk_mov_b32 v[22:23], v[48:49], v[46:47] op_sel:[1,0]
	v_mov_b32_e32 v49, v47
	v_pk_add_f32 v[22:23], v[22:23], 0 op_sel_hi:[1,0]
	v_pk_mul_f32 v[18:19], v[16:17], v[16:17]
	v_pk_add_f32 v[22:23], v[48:49], v[22:23]
	v_ashrrev_i32_e32 v72, 4, v130
	v_pk_add_f32 v[22:23], v[26:27], v[22:23]
	v_lshlrev_b32_e32 v77, 2, v72
	v_pk_add_f32 v[22:23], v[36:37], v[22:23]
	v_mov_b32_e32 v36, v57
	v_mul_f32_e32 v26, 0xbfb8aa3b, v23
	v_exp_f32_e32 v28, v26
	v_mul_f32_e32 v26, 0xbfb8aa3b, v22
	v_exp_f32_e32 v34, v26
	v_mov_b32_e32 v37, v55
	v_add_f32_e32 v28, 1.0, v28
	v_rcp_f32_e32 v29, v28
	v_add_f32_e32 v28, 1.0, v34
	v_mov_b32_e32 v34, v61
	v_pk_add_f32 v[34:35], v[34:35], 0 op_sel_hi:[1,0]
	v_mov_b32_e32 v61, v58
	v_pk_add_f32 v[34:35], v[60:61], v[34:35]
	v_mov_b32_e32 v57, v54
	v_pk_add_f32 v[34:35], v[36:37], v[34:35]
	v_rcp_f32_e32 v28, v28
	v_pk_add_f32 v[34:35], v[56:57], v[34:35]
	v_pk_mul_f32 v[26:27], v[20:21], v[20:21]
	v_mul_f32_e32 v36, 0xbfb8aa3b, v35
	v_exp_f32_e32 v36, v36
	v_mul_f32_e32 v37, 0xbfb8aa3b, v34
	v_exp_f32_e32 v37, v37
	v_pk_mul_f32 v[22:23], v[22:23], v[28:29]
	v_add_f32_e32 v28, 1.0, v36
	v_rcp_f32_e32 v29, v28
	v_add_f32_e32 v28, 1.0, v37
	v_mov_b32_e32 v36, v41
	v_mov_b32_e32 v37, v39
	v_pk_add_f32 v[36:37], v[36:37], 0 op_sel_hi:[1,0]
	v_mov_b32_e32 v41, v38
	v_pk_add_f32 v[36:37], v[40:41], v[36:37]
	v_mov_b32_e32 v38, v33
	v_mov_b32_e32 v39, v31
	v_pk_add_f32 v[36:37], v[38:39], v[36:37]
	v_mov_b32_e32 v33, v30
	v_pk_add_f32 v[30:31], v[32:33], v[36:37]
	v_rcp_f32_e32 v28, v28
	v_mul_f32_e32 v32, 0xbfb8aa3b, v31
	v_exp_f32_e32 v32, v32
	v_mul_f32_e32 v33, 0xbfb8aa3b, v30
	v_exp_f32_e32 v36, v33
	v_mov_b32_e32 v38, v12
	v_add_f32_e32 v32, 1.0, v32
	v_rcp_f32_e32 v33, v32
	v_add_f32_e32 v32, 1.0, v36
	v_rcp_f32_e32 v32, v32
	v_mov_b32_e32 v39, v14
	v_mov_b32_e32 v14, v13
	v_pk_add_f32 v[12:13], v[38:39], v[14:15]
	v_mov_b32_e32 v14, v19
	v_mov_b32_e32 v15, v25
	v_pk_mul_f32 v[36:37], v[22:23], v[22:23]
	v_pk_add_f32 v[12:13], v[14:15], v[12:13]
	v_mov_b32_e32 v19, v24
	v_pk_mul_f32 v[28:29], v[34:35], v[28:29]
	v_pk_mul_f32 v[30:31], v[30:31], v[32:33]
	v_pk_add_f32 v[12:13], v[18:19], v[12:13]
	v_mov_b32_e32 v14, v37
	v_mov_b32_e32 v15, v27
	v_pk_mul_f32 v[34:35], v[28:29], v[28:29]
	v_pk_mul_f32 v[32:33], v[30:31], v[30:31]
	v_pk_add_f32 v[12:13], v[14:15], v[12:13]
	v_mov_b32_e32 v37, v26
	v_pk_add_f32 v[12:13], v[36:37], v[12:13]
	v_mov_b32_e32 v14, v33
	v_mov_b32_e32 v15, v35
	v_pk_add_f32 v[12:13], v[14:15], v[12:13]
	v_mov_b32_e32 v33, v34
	v_pk_add_f32 v[12:13], v[32:33], v[12:13]
	ds_bpermute_b32 v15, v197, v13
	ds_bpermute_b32 v14, v197, v12
	v_mul_f32_e32 v18, 0xbfb8aa3b, v78
	v_mul_f32_e32 v19, 0xbfb8aa3b, v79
	v_exp_f32_e32 v18, v18
	v_exp_f32_e32 v19, v19
	s_waitcnt lgkmcnt(0)
; #define LAS __attribute__((address_space(3)))
; __device__ __forceinline__ bf16_t f2bf(float f) { return (bf16_t)(pk2(f, 0.f) & 0xffffu); }
; __device__ __forceinline__ float fexp(float x) { return __expf(x); }
; __device__ __forceinline__ u32x4 pack8(const float (&f)[8]) { u32x4 w; w.x = pk2(f[0], f[1]); w.y = pk2(f[2], f[3]); w.z = pk2(f[4], f[5]); w.w = pk2(f[6], f[7]); return w; }
; #define LBAR() do { asm volatile("s_waitcnt lgkmcnt(0)" ::: "memory"); __builtin_amdgcn_s_barrier(); asm volatile("" ::: "memory"); } while (0)
; __device__ __forceinline__ void gdn_unit(const Ctx& X, LAS unsigned char* hl, int b, int c, int h, int tid_h, int w4, int lane, int layer) {
;     ...
;             const float rq = 0.125f * rsqrtf(sq + 1e-6f), rk = rsqrtf(sk + 1e-6f), kd = rk * fexp(G63 - Gi);
;             float t8[8];
; #pragma unroll
;             for (int e = 0; e < 8; ++e) t8[e] = y[0][e] * rq;
;             *(LAS u32x4*)(Q + i * LT + cseg * 8) = pack8(t8);
; #pragma unroll
;             for (int e = 0; e < 8; ++e) t8[e] = y[1][e] * rk;
;             *(LAS u32x4*)(K + i * LT + cseg * 8) = pack8(t8);
; #pragma unroll
;             for (int e = 0; e < 8; ++e) t8[e] = y[1][e] * rk * bi;
;             *(LAS u32x4*)(KB + i * LT + cseg * 8) = pack8(t8);
;             *(LAS u32x4*)(V + i * LT + cseg * 8) = pack8(y[2]);
; #pragma unroll
;             for (int e = 0; e < 8; ++e) KDT[(cseg * 8 + e) * LT + i] = f2bf(y[1][e] * kd);
;         }
;     }
;     LBAR();
;     }
;     {
;         f32x4 aA[4], aP[4];
; #pragma unroll
;         for (int ct = 0; ct < 4; ++ct) { aA[ct] = mma16(KB, 16 * w4, K, 16 * ct, (f32x4){0.f, 0.f, 0.f, 0.f}, r, q); aP[ct] = mma16(Q, 16 * w4, K, 16 * ct, (f32x4){0.f, 0.f, 0.f, 0.f}, r, q); }
; #pragma unroll
;         for (int ct = 0; ct < 4; ++ct)
; #pragma unroll
;             for (int j = 0; j < 4; ++j) { const int ii = 16 * w4 + 4 * q + j, col = 16 * ct + r;
;                 const float L = fexp(fminf(Gs[ii] - Gs[col], 0.f));
;                 AB[ii * LT + col] = f2bf(ii > col ? aA[ct][j] * L : 0.f);
;                 P[ii * LT + col] = f2bf(ii >= col ? aP[ct][j] * L : 0.f); }
;     }
	v_pk_add_f32 v[12:13], v[12:13], v[14:15]
	ds_bpermute_b32 v15, v196, v13
	ds_bpermute_b32 v14, v196, v12
	v_add_f32_e32 v18, 1.0, v18
	v_add_f32_e32 v19, 1.0, v19
	v_rcp_f32_e32 v18, v18
	v_rcp_f32_e32 v19, v19
	s_waitcnt lgkmcnt(0)
	v_pk_add_f32 v[12:13], v[12:13], v[14:15]
	ds_bpermute_b32 v15, v195, v13
	ds_bpermute_b32 v14, v195, v12
	v_mul_f32_e32 v24, v44, v86
	v_mul_f32_e32 v25, v45, v87
	v_mul_f32_e32 v18, v78, v18
	v_mul_f32_e32 v19, v79, v19
	s_waitcnt lgkmcnt(0)
	v_pk_add_f32 v[12:13], v[12:13], v[14:15]
	v_sub_f32_e32 v15, v194, v110
	v_pk_add_f32 v[12:13], v[12:13], s[4:5] op_sel_hi:[1,0]
	v_mul_f32_e32 v15, 0x3fb8aa3b, v15
	v_mul_f32_e32 v14, 0x4b800000, v13
	v_cmp_gt_f32_e32 vcc, s3, v13
	v_cmp_gt_f32_e64 s[0:1], s3, v12
	v_exp_f32_e32 v15, v15
	v_cndmask_b32_e32 v13, v13, v14, vcc
	v_rsq_f32_e32 v13, v13
	v_mul_f32_e32 v14, 0x4b800000, v12
	v_cndmask_b32_e64 v12, v12, v14, s[0:1]
	v_rsq_f32_e32 v12, v12
	v_mul_f32_e32 v14, 0x45800000, v13
	v_cndmask_b32_e32 v13, v13, v14, vcc
	v_mul_f32_e32 v13, 0x3e000000, v13
	v_mul_f32_e32 v8, v8, v13
	v_mul_f32_e32 v9, v9, v13
	v_mul_f32_e32 v11, v11, v13
	v_mul_f32_e32 v10, v10, v13
	v_mul_f32_e32 v21, v21, v13
	v_mul_f32_e32 v20, v20, v13
	v_mul_f32_e32 v26, v29, v13
	v_mul_f32_e32 v13, v28, v13
	v_mul_f32_e32 v14, 0x45800000, v12
	v_cvt_pk_bf16_f32 v8, v8, v9
	v_cvt_pk_bf16_f32 v9, v11, v10
	v_cvt_pk_bf16_f32 v10, v21, v20
	v_cvt_pk_bf16_f32 v11, v26, v13
	v_add_u32_e32 v13, 0x1200, v108
	v_cndmask_b32_e64 v12, v12, v14, s[0:1]
	v_add_u32_e32 v14, v193, v13
	ds_write_b128 v14, v[8:11]
	v_mul_f32_e32 v14, v6, v12
	v_mul_f32_e32 v20, v7, v12
	v_mul_f32_e32 v21, v17, v12
	v_mul_f32_e32 v26, v16, v12
	v_mul_f32_e32 v27, v23, v12
	v_mul_f32_e32 v28, v22, v12
	v_mul_f32_e32 v29, v31, v12
	v_mul_f32_e32 v32, v30, v12
	v_cvt_pk_bf16_f32 v8, v14, v20
	v_cvt_pk_bf16_f32 v9, v21, v26
	v_cvt_pk_bf16_f32 v10, v27, v28
	v_cvt_pk_bf16_f32 v11, v29, v32
	v_add_u32_e32 v33, v192, v13
	ds_write_b128 v33, v[8:11]
	v_mul_f32_e32 v8, v109, v14
	v_mul_f32_e32 v9, v109, v20
	v_mul_f32_e32 v10, v109, v21
	v_mul_f32_e32 v11, v109, v26
	v_mul_f32_e32 v14, v109, v27
	v_mul_f32_e32 v12, v15, v12
	v_mul_f32_e32 v20, v109, v28
	v_mul_f32_e32 v21, v109, v29
	v_mul_f32_e32 v26, v109, v32
	v_cvt_pk_bf16_f32 v8, v8, v9
	v_cvt_pk_bf16_f32 v9, v10, v11
	v_cvt_pk_bf16_f32 v10, v14, v20
	v_cvt_pk_bf16_f32 v11, v21, v26
	v_add_u32_e32 v14, v155, v13
	v_add_u32_e32 v13, v133, v13
	v_mul_f32_e32 v6, v6, v12
	ds_write_b128 v14, v[8:11]
	v_cvt_pk_bf16_f32 v8, v82, v83
	v_cvt_pk_bf16_f32 v9, v84, v85
	v_cvt_pk_bf16_f32 v10, v24, v25
	v_cvt_pk_bf16_f32 v11, v18, v19
	ds_write_b128 v13, v[8:11]
	v_cvt_pk_bf16_f32 v6, v6, v157
	ds_write_b16 v107, v6 offset:64
	v_mul_f32_e32 v6, v7, v12
	v_cvt_pk_bf16_f32 v6, v6, v157
	ds_write_b16 v107, v6 offset:208
	v_mul_f32_e32 v6, v17, v12
	v_cvt_pk_bf16_f32 v6, v6, v157
	ds_write_b16 v107, v6 offset:352
	v_mul_f32_e32 v6, v16, v12
	v_cvt_pk_bf16_f32 v6, v6, v157
	ds_write_b16 v107, v6 offset:496
	v_mul_f32_e32 v6, v23, v12
	v_cvt_pk_bf16_f32 v6, v6, v157
	ds_write_b16 v107, v6 offset:640
	v_mul_f32_e32 v6, v22, v12
	v_cvt_pk_bf16_f32 v6, v6, v157
	ds_write_b16 v107, v6 offset:784
	v_mul_f32_e32 v6, v31, v12
	v_cvt_pk_bf16_f32 v6, v6, v157
	ds_write_b16 v107, v6 offset:928
	v_mul_f32_e32 v6, v30, v12
	v_cvt_pk_bf16_f32 v6, v6, v157
	ds_write_b16 v107, v6 offset:1072
	v_or_b32_e32 v6, s39, v106
	v_mul_u32_u24_e32 v78, 0x90, v6
	v_and_b32_e32 v14, -16, v130
	v_mul_u32_u24_e32 v82, 0x90, v106
	s_waitcnt lgkmcnt(0)
	s_barrier
	v_bfe_u32 v6, v224, 6, 2
	v_and_b32_e32 v7, 15, v232
	v_lshrrev_b32_e32 v8, 4, v232
	v_lshl_or_b32 v9, v6, 4, v7
	v_mul_u32_u24_e32 v10, 0x90, v9
	v_mul_u32_u24_e32 v11, 0x90, v7
	v_lshl_add_u32 v13, v8, 4, v10
	v_lshl_add_u32 v11, v8, 4, v11
	v_add_u32_e32 v13, v182, v13
	v_add_u32_e32 v11, v182, v11
	v_add_u32_e32 v15, 0x4800, v13
	v_add_u32_e32 v11, 0x2400, v11
	ds_read_b128 v[16:19], v15
	ds_read_b128 v[20:23], v15 offset:64
	ds_read_b128 v[24:27], v13
	ds_read_b128 v[28:31], v13 offset:64
	ds_read_b128 v[32:35], v11
	ds_read_b128 v[36:39], v11 offset:64
	ds_read_b128 v[40:43], v11 offset:2304
	ds_read_b128 v[44:47], v11 offset:2368
	ds_read_b128 v[48:51], v11 offset:4608
	ds_read_b128 v[52:55], v11 offset:4672
	ds_read_b128 v[56:59], v11 offset:6912
	ds_read_b128 v[60:63], v11 offset:6976
	v_lshl_add_u32 v66, v9, 2, v185
	v_lshl_add_u32 v67, v8, 4, v185
	ds_read_b32 v64, v66
	ds_read_b128 v[136:139], v67
	ds_read_b128 v[140:143], v67 offset:64
	v_lshlrev_b32_e32 v12, 2, v8
	v_sub_u32_e32 v12, v9, v12
	v_lshl_add_u32 v65, v8, 3, v10
	v_add_u32_e32 v68, v186, v65
	v_add_u32_e32 v69, v184, v65
	s_waitcnt lgkmcnt(3)
	v_mfma_f32_16x16x32_bf16 v[190:193], v[32:35], v[16:19], 0
	v_mfma_f32_16x16x32_bf16 v[206:209], v[32:35], v[24:27], 0
	v_mfma_f32_16x16x32_bf16 v[194:197], v[40:43], v[16:19], 0
	v_mfma_f32_16x16x32_bf16 v[210:213], v[40:43], v[24:27], 0
	v_mfma_f32_16x16x32_bf16 v[198:201], v[48:51], v[16:19], 0
	v_mfma_f32_16x16x32_bf16 v[214:217], v[48:51], v[24:27], 0
	v_mfma_f32_16x16x32_bf16 v[202:205], v[56:59], v[16:19], 0
	v_mfma_f32_16x16x32_bf16 v[218:221], v[56:59], v[24:27], 0
	ds_read_b128 v[144:147], v67 offset:128
	ds_read_b128 v[148:151], v67 offset:192
	v_mfma_f32_16x16x32_bf16 v[190:193], v[36:39], v[20:23], v[190:193]
	v_mfma_f32_16x16x32_bf16 v[206:209], v[36:39], v[28:31], v[206:209]
	v_mfma_f32_16x16x32_bf16 v[194:197], v[44:47], v[20:23], v[194:197]
	v_mfma_f32_16x16x32_bf16 v[210:213], v[44:47], v[28:31], v[210:213]
	v_mfma_f32_16x16x32_bf16 v[198:201], v[52:55], v[20:23], v[198:201]
	v_mfma_f32_16x16x32_bf16 v[214:217], v[52:55], v[28:31], v[214:217]
	v_mfma_f32_16x16x32_bf16 v[202:205], v[60:63], v[20:23], v[202:205]
	v_mfma_f32_16x16x32_bf16 v[218:221], v[60:63], v[28:31], v[218:221]
	v_readlane_b32 s0, v252, 48
	v_readlane_b32 s1, v252, 49
	s_waitcnt lgkmcnt(0)
; __device__ __forceinline__ bf16_t f2bf(float f) { return (bf16_t)(pk2(f, 0.f) & 0xffffu); }
; __device__ __forceinline__ float fexp(float x) { return __expf(x); }
; #define LBAR() do { asm volatile("s_waitcnt lgkmcnt(0)" ::: "memory"); __builtin_amdgcn_s_barrier(); asm volatile("" ::: "memory"); } while (0)
; __device__ __forceinline__ void gdn_unit(const Ctx& X, LAS unsigned char* hl, int b, int c, int h, int tid_h, int w4, int lane, int layer) {
;     ...
;         for (int ct = 0; ct < 4; ++ct)
; #pragma unroll
;             for (int j = 0; j < 4; ++j) { const int ii = 16 * w4 + 4 * q + j, col = 16 * ct + r;
;                 const float L = fexp(fminf(Gs[ii] - Gs[col], 0.f));
;                 AB[ii * LT + col] = f2bf(ii > col ? aA[ct][j] * L : 0.f);
;                 P[ii * LT + col] = f2bf(ii >= col ? aP[ct][j] * L : 0.f); }
;     }
;     LBAR();
	v_sub_f32_e32 v70, v64, v136
	v_sub_f32_e32 v71, v64, v137
	v_sub_f32_e32 v73, v64, v138
	v_sub_f32_e32 v74, v64, v139
	v_min_f32_e32 v70, 0, v70
	v_min_f32_e32 v71, 0, v71
	v_min_f32_e32 v73, 0, v73
	v_min_f32_e32 v74, 0, v74
	v_mul_f32_e32 v70, 0x3fb8aa3b, v70
	v_mul_f32_e32 v71, 0x3fb8aa3b, v71
	v_mul_f32_e32 v73, 0x3fb8aa3b, v73
	v_mul_f32_e32 v74, 0x3fb8aa3b, v74
	v_exp_f32_e32 v70, v70
	v_exp_f32_e32 v71, v71
	v_exp_f32_e32 v73, v73
	v_exp_f32_e32 v74, v74
	v_cmp_lt_i32_e32 vcc, 0, v12
	v_cmp_lt_i32_e64 s[4:5], 1, v12
	v_cmp_lt_i32_e64 s[6:7], 2, v12
	v_cmp_lt_i32_e64 s[24:25], 3, v12
	v_mul_f32_e32 v75, v190, v70
	v_mul_f32_e32 v76, v191, v71
	v_mul_f32_e32 v79, v192, v73
	v_mul_f32_e32 v80, v193, v74
	v_mul_f32_e32 v81, v206, v70
	v_mul_f32_e32 v83, v207, v71
	v_mul_f32_e32 v84, v208, v73
	v_mul_f32_e32 v114, v209, v74
	v_cndmask_b32_e32 v75, 0, v75, vcc
	v_cndmask_b32_e64 v76, 0, v76, s[4:5]
	v_cndmask_b32_e64 v79, 0, v79, s[6:7]
	v_cndmask_b32_e64 v80, 0, v80, s[24:25]
	v_cmp_le_i32_e32 vcc, 0, v12
	v_cmp_le_i32_e64 s[4:5], 1, v12
	v_cmp_le_i32_e64 s[6:7], 2, v12
	v_cmp_le_i32_e64 s[24:25], 3, v12
	v_cvt_pk_bf16_f32 v116, v75, v76
	v_cvt_pk_bf16_f32 v117, v79, v80
	ds_write_b64 v68, v[116:117]
	v_cndmask_b32_e32 v81, 0, v81, vcc
	v_cndmask_b32_e64 v83, 0, v83, s[4:5]
	v_cndmask_b32_e64 v84, 0, v84, s[6:7]
	v_cndmask_b32_e64 v114, 0, v114, s[24:25]
	v_cvt_pk_bf16_f32 v152, v81, v83
	v_cvt_pk_bf16_f32 v153, v84, v114
	ds_write_b64 v69, v[152:153]
	v_sub_f32_e32 v70, v64, v140
	v_sub_f32_e32 v71, v64, v141
	v_sub_f32_e32 v73, v64, v142
	v_sub_f32_e32 v74, v64, v143
	v_min_f32_e32 v70, 0, v70
	v_min_f32_e32 v71, 0, v71
	v_min_f32_e32 v73, 0, v73
	v_min_f32_e32 v74, 0, v74
	v_mul_f32_e32 v70, 0x3fb8aa3b, v70
	v_mul_f32_e32 v71, 0x3fb8aa3b, v71
	v_mul_f32_e32 v73, 0x3fb8aa3b, v73
	v_mul_f32_e32 v74, 0x3fb8aa3b, v74
	v_exp_f32_e32 v70, v70
	v_exp_f32_e32 v71, v71
	v_exp_f32_e32 v73, v73
	v_exp_f32_e32 v74, v74
	v_cmp_lt_i32_e32 vcc, 16, v12
	v_cmp_lt_i32_e64 s[4:5], 17, v12
	v_cmp_lt_i32_e64 s[6:7], 18, v12
	v_cmp_lt_i32_e64 s[24:25], 19, v12
	v_mul_f32_e32 v75, v194, v70
	v_mul_f32_e32 v76, v195, v71
	v_mul_f32_e32 v79, v196, v73
	v_mul_f32_e32 v80, v197, v74
	v_mul_f32_e32 v81, v210, v70
	v_mul_f32_e32 v83, v211, v71
	v_mul_f32_e32 v84, v212, v73
	v_mul_f32_e32 v114, v213, v74
	v_cndmask_b32_e32 v75, 0, v75, vcc
	v_cndmask_b32_e64 v76, 0, v76, s[4:5]
	v_cndmask_b32_e64 v79, 0, v79, s[6:7]
	v_cndmask_b32_e64 v80, 0, v80, s[24:25]
	v_cmp_le_i32_e32 vcc, 16, v12
	v_cmp_le_i32_e64 s[4:5], 17, v12
	v_cmp_le_i32_e64 s[6:7], 18, v12
	v_cmp_le_i32_e64 s[24:25], 19, v12
	v_cvt_pk_bf16_f32 v116, v75, v76
	v_cvt_pk_bf16_f32 v117, v79, v80
	ds_write_b64 v68, v[116:117] offset:32
	v_cndmask_b32_e32 v81, 0, v81, vcc
	v_cndmask_b32_e64 v83, 0, v83, s[4:5]
	v_cndmask_b32_e64 v84, 0, v84, s[6:7]
	v_cndmask_b32_e64 v114, 0, v114, s[24:25]
	v_cvt_pk_bf16_f32 v152, v81, v83
	v_cvt_pk_bf16_f32 v153, v84, v114
	ds_write_b64 v69, v[152:153] offset:32
	v_sub_f32_e32 v70, v64, v144
	v_sub_f32_e32 v71, v64, v145
	v_sub_f32_e32 v73, v64, v146
	v_sub_f32_e32 v74, v64, v147
	v_min_f32_e32 v70, 0, v70
	v_min_f32_e32 v71, 0, v71
	v_min_f32_e32 v73, 0, v73
	v_min_f32_e32 v74, 0, v74
	v_mul_f32_e32 v70, 0x3fb8aa3b, v70
	v_mul_f32_e32 v71, 0x3fb8aa3b, v71
	v_mul_f32_e32 v73, 0x3fb8aa3b, v73
	v_mul_f32_e32 v74, 0x3fb8aa3b, v74
	v_exp_f32_e32 v70, v70
	v_exp_f32_e32 v71, v71
	v_exp_f32_e32 v73, v73
	v_exp_f32_e32 v74, v74
	v_cmp_lt_i32_e32 vcc, 32, v12
	v_cmp_lt_i32_e64 s[4:5], 33, v12
	v_cmp_lt_i32_e64 s[6:7], 34, v12
	v_cmp_lt_i32_e64 s[24:25], 35, v12
	v_mul_f32_e32 v75, v198, v70
	v_mul_f32_e32 v76, v199, v71
	v_mul_f32_e32 v79, v200, v73
	v_mul_f32_e32 v80, v201, v74
	v_mul_f32_e32 v81, v214, v70
	v_mul_f32_e32 v83, v215, v71
	v_mul_f32_e32 v84, v216, v73
	v_mul_f32_e32 v114, v217, v74
	v_cndmask_b32_e32 v75, 0, v75, vcc
	v_cndmask_b32_e64 v76, 0, v76, s[4:5]
	v_cndmask_b32_e64 v79, 0, v79, s[6:7]
	v_cndmask_b32_e64 v80, 0, v80, s[24:25]
	v_cmp_le_i32_e32 vcc, 32, v12
	v_cmp_le_i32_e64 s[4:5], 33, v12
	v_cmp_le_i32_e64 s[6:7], 34, v12
	v_cmp_le_i32_e64 s[24:25], 35, v12
	v_cvt_pk_bf16_f32 v116, v75, v76
	v_cvt_pk_bf16_f32 v117, v79, v80
	ds_write_b64 v68, v[116:117] offset:64
	v_cndmask_b32_e32 v81, 0, v81, vcc
	v_cndmask_b32_e64 v83, 0, v83, s[4:5]
	v_cndmask_b32_e64 v84, 0, v84, s[6:7]
	v_cndmask_b32_e64 v114, 0, v114, s[24:25]
	v_cvt_pk_bf16_f32 v152, v81, v83
	v_cvt_pk_bf16_f32 v153, v84, v114
	ds_write_b64 v69, v[152:153] offset:64
	v_sub_f32_e32 v70, v64, v148
	v_sub_f32_e32 v71, v64, v149
	v_sub_f32_e32 v73, v64, v150
	v_sub_f32_e32 v74, v64, v151
	v_min_f32_e32 v70, 0, v70
	v_min_f32_e32 v71, 0, v71
	v_min_f32_e32 v73, 0, v73
	v_min_f32_e32 v74, 0, v74
	v_mul_f32_e32 v70, 0x3fb8aa3b, v70
	v_mul_f32_e32 v71, 0x3fb8aa3b, v71
	v_mul_f32_e32 v73, 0x3fb8aa3b, v73
	v_mul_f32_e32 v74, 0x3fb8aa3b, v74
	v_exp_f32_e32 v70, v70
	v_exp_f32_e32 v71, v71
	v_exp_f32_e32 v73, v73
	v_exp_f32_e32 v74, v74
	v_cmp_lt_i32_e32 vcc, 48, v12
	v_cmp_lt_i32_e64 s[4:5], 49, v12
	v_cmp_lt_i32_e64 s[6:7], 50, v12
	v_cmp_lt_i32_e64 s[24:25], 51, v12
	v_mul_f32_e32 v75, v202, v70
	v_mul_f32_e32 v76, v203, v71
	v_mul_f32_e32 v79, v204, v73
	v_mul_f32_e32 v80, v205, v74
	v_mul_f32_e32 v81, v218, v70
	v_mul_f32_e32 v83, v219, v71
	v_mul_f32_e32 v84, v220, v73
	v_mul_f32_e32 v114, v221, v74
	v_cndmask_b32_e32 v75, 0, v75, vcc
	v_cndmask_b32_e64 v76, 0, v76, s[4:5]
	v_cndmask_b32_e64 v79, 0, v79, s[6:7]
	v_cndmask_b32_e64 v80, 0, v80, s[24:25]
	v_cmp_le_i32_e32 vcc, 48, v12
	v_cmp_le_i32_e64 s[4:5], 49, v12
	v_cmp_le_i32_e64 s[6:7], 50, v12
	v_cmp_le_i32_e64 s[24:25], 51, v12
	v_cvt_pk_bf16_f32 v116, v75, v76
	v_cvt_pk_bf16_f32 v117, v79, v80
	ds_write_b64 v68, v[116:117] offset:96
	v_cndmask_b32_e32 v81, 0, v81, vcc
	v_cndmask_b32_e64 v83, 0, v83, s[4:5]
	v_cndmask_b32_e64 v84, 0, v84, s[6:7]
	v_cndmask_b32_e64 v114, 0, v114, s[24:25]
	v_cvt_pk_bf16_f32 v152, v81, v83
	v_cvt_pk_bf16_f32 v153, v84, v114
	ds_write_b64 v69, v[152:153] offset:96
	s_waitcnt lgkmcnt(0)
	s_barrier
; #define LAS __attribute__((address_space(3)))
; __device__ __forceinline__ float bf2f(bf16_t b) { return __uint_as_float((unsigned)b << 16); }
; __device__ __forceinline__ float fexp(float x) { return __expf(x); }
; #define LBAR() do { asm volatile("s_waitcnt lgkmcnt(0)" ::: "memory"); __builtin_amdgcn_s_barrier(); asm volatile("" ::: "memory"); } while (0)
; __device__ __forceinline__ void gdn_unit(const Ctx& X, LAS unsigned char* hl, int b, int c, int h, int tid_h, int w4, int lane, int layer) {
;     ...
;     LBAR();
;     float rc[64];
;     if (w4 < 2) {
;         const int col = tid_h & 63; const LAS bf16_t* src = w4 == 0 ? V : KB;
; #pragma unroll
;         for (int i = 0; i < 64; ++i) { const float sc = w4 == 0 ? Bs[i] : fexp(Gs[i]); rc[i] = bf2f(src[i * LT + col]) * sc; }
;     }
	v_cndmask_b32_e64 v6, 0, 1, s[0:1]
	v_cmp_ne_u32_e64 s[4:5], 1, v6
	s_andn2_b64 vcc, exec, s[0:1]
	s_cbranch_vccnz .LBB0_608
	v_readlane_b32 s6, v252, 46
	v_readlane_b32 s7, v252, 47
	v_and_b32_e32 v7, 63, v132
	v_cndmask_b32_e64 v8, v183, v181, s[40:41]
	v_lshl_add_u32 v8, v7, 1, v8
	s_and_b64 vcc, exec, s[6:7]
	s_cbranch_vccz .Lrc_bs
	ds_read_b32 v6, v185
	ds_read_b32 v9, v185 offset:4
	ds_read_b32 v11, v185 offset:8
	ds_read_b32 v13, v185 offset:12
	ds_read_b32 v15, v185 offset:16
	ds_read_b32 v17, v185 offset:20
	ds_read_b32 v19, v185 offset:24
	ds_read_b32 v26, v185 offset:28
	ds_read_b32 v29, v185 offset:32
	ds_read_b32 v32, v185 offset:36
	ds_read_b32 v30, v185 offset:40
	ds_read_b32 v35, v185 offset:44
	ds_read_b32 v28, v185 offset:48
	ds_read_b32 v38, v185 offset:52
	ds_read_b32 v40, v185 offset:56
	ds_read_b32 v42, v185 offset:60
	ds_read_b32 v25, v185 offset:64
	ds_read_b32 v45, v185 offset:68
	ds_read_b32 v47, v185 offset:72
	ds_read_b32 v49, v185 offset:76
	ds_read_b32 v51, v185 offset:80
	ds_read_b32 v53, v185 offset:84
	ds_read_b32 v55, v185 offset:88
	ds_read_b32 v57, v185 offset:92
	ds_read_b32 v59, v185 offset:96
	ds_read_b32 v61, v185 offset:100
	ds_read_b32 v63, v185 offset:104
	ds_read_b32 v65, v185 offset:108
	ds_read_b32 v67, v185 offset:112
	ds_read_b32 v69, v185 offset:116
	ds_read_b32 v71, v185 offset:120
	ds_read_b32 v24, v185 offset:124
	ds_read_b32 v23, v185 offset:128
	ds_read_b32 v113, v185 offset:132
	ds_read_b32 v112, v185 offset:136
	ds_read_b32 v111, v185 offset:140
	ds_read_b32 v110, v185 offset:144
	ds_read_b32 v109, v185 offset:148
	ds_read_b32 v108, v185 offset:152
	ds_read_b32 v107, v185 offset:156
	ds_read_b32 v105, v185 offset:160
	ds_read_b32 v104, v185 offset:164
	ds_read_b32 v103, v185 offset:168
	ds_read_b32 v102, v185 offset:172
	ds_read_b32 v101, v185 offset:176
	ds_read_b32 v100, v185 offset:180
	ds_read_b32 v99, v185 offset:184
	ds_read_b32 v22, v185 offset:188
	ds_read_b32 v21, v185 offset:192
	ds_read_b32 v98, v185 offset:196
	ds_read_b32 v97, v185 offset:200
	ds_read_b32 v96, v185 offset:204
	ds_read_b32 v95, v185 offset:208
	ds_read_b32 v94, v185 offset:212
	ds_read_b32 v93, v185 offset:216
	ds_read_b32 v92, v185 offset:220
	ds_read_b32 v91, v185 offset:224
	ds_read_b32 v90, v185 offset:228
	ds_read_b32 v89, v185 offset:232
	ds_read_b32 v88, v185 offset:236
	ds_read_b32 v87, v185 offset:240
	ds_read_b32 v86, v185 offset:244
	ds_read_b32 v85, v185 offset:248
	ds_read_b32 v144, v185 offset:252
	ds_read_u16 v7, v8
	ds_read_u16 v10, v8 offset:144
	ds_read_u16 v12, v8 offset:288
	ds_read_u16 v14, v8 offset:432
	ds_read_u16 v16, v8 offset:576
	ds_read_u16 v18, v8 offset:720
	ds_read_u16 v20, v8 offset:864
	ds_read_u16 v27, v8 offset:1008
	ds_read_u16 v31, v8 offset:1152
	ds_read_u16 v33, v8 offset:1296
	ds_read_u16 v34, v8 offset:1440
	ds_read_u16 v36, v8 offset:1584
	ds_read_u16 v37, v8 offset:1728
	ds_read_u16 v39, v8 offset:1872
	ds_read_u16 v41, v8 offset:2016
	ds_read_u16 v43, v8 offset:2160
	ds_read_u16 v44, v8 offset:2304
	ds_read_u16 v46, v8 offset:2448
	ds_read_u16 v48, v8 offset:2592
	ds_read_u16 v50, v8 offset:2736
	ds_read_u16 v52, v8 offset:2880
	ds_read_u16 v54, v8 offset:3024
	ds_read_u16 v56, v8 offset:3168
	ds_read_u16 v58, v8 offset:3312
	ds_read_u16 v60, v8 offset:3456
	ds_read_u16 v62, v8 offset:3600
	ds_read_u16 v64, v8 offset:3744
	ds_read_u16 v66, v8 offset:3888
	ds_read_u16 v68, v8 offset:4032
	ds_read_u16 v70, v8 offset:4176
	ds_read_u16 v84, v8 offset:4320
	ds_read_u16 v114, v8 offset:4464
	ds_read_u16 v115, v8 offset:4608
	ds_read_u16 v116, v8 offset:4752
	ds_read_u16 v117, v8 offset:4896
	ds_read_u16 v118, v8 offset:5040
	ds_read_u16 v119, v8 offset:5184
	ds_read_u16 v120, v8 offset:5328
	ds_read_u16 v121, v8 offset:5472
	ds_read_u16 v122, v8 offset:5616
	ds_read_u16 v123, v8 offset:5760
	ds_read_u16 v124, v8 offset:5904
	ds_read_u16 v125, v8 offset:6048
	ds_read_u16 v126, v8 offset:6192
	ds_read_u16 v127, v8 offset:6336
	ds_read_u16 v128, v8 offset:6480
	ds_read_u16 v129, v8 offset:6624
	ds_read_u16 v133, v8 offset:6768
	ds_read_u16 v134, v8 offset:6912
	ds_read_u16 v135, v8 offset:7056
	ds_read_u16 v136, v8 offset:7200
	ds_read_u16 v137, v8 offset:7344
	ds_read_u16 v138, v8 offset:7488
	ds_read_u16 v139, v8 offset:7632
	ds_read_u16 v140, v8 offset:7776
	ds_read_u16 v141, v8 offset:7920
	ds_read_u16 v142, v8 offset:8064
	ds_read_u16 v143, v8 offset:8208
	ds_read_u16 v145, v8 offset:8352
	ds_read_u16 v146, v8 offset:8496
	ds_read_u16 v147, v8 offset:8640
	ds_read_u16 v148, v8 offset:8784
	ds_read_u16 v149, v8 offset:8928
	s_waitcnt lgkmcnt(15)
; #define LAS __attribute__((address_space(3)))
; __device__ __forceinline__ float bf2f(bf16_t b) { return __uint_as_float((unsigned)b << 16); }
; __device__ __forceinline__ float fexp(float x) { return __expf(x); }
; __device__ __forceinline__ void gdn_unit(const Ctx& X, LAS unsigned char* hl, int b, int c, int h, int tid_h, int w4, int lane, int layer) {
;     ...
;     if (w4 < 2) {
;         const int col = tid_h & 63; const LAS bf16_t* src = w4 == 0 ? V : KB;
; #pragma unroll
;         for (int i = 0; i < 64; ++i) { const float sc = w4 == 0 ? Bs[i] : fexp(Gs[i]); rc[i] = bf2f(src[i * LT + col]) * sc; }
;     }
	v_mul_f32_e32 v6, 0x3fb8aa3b, v6
	v_exp_f32_e32 v6, v6
	v_mul_f32_e32 v9, 0x3fb8aa3b, v9
	v_exp_f32_e32 v9, v9
	v_mul_f32_e32 v11, 0x3fb8aa3b, v11
	v_exp_f32_e32 v11, v11
	v_mul_f32_e32 v13, 0x3fb8aa3b, v13
	v_exp_f32_e32 v13, v13
	v_mul_f32_e32 v15, 0x3fb8aa3b, v15
	v_exp_f32_e32 v15, v15
	v_mul_f32_e32 v17, 0x3fb8aa3b, v17
	v_exp_f32_e32 v17, v17
	v_mul_f32_e32 v19, 0x3fb8aa3b, v19
	v_exp_f32_e32 v19, v19
	v_mul_f32_e32 v26, 0x3fb8aa3b, v26
	v_exp_f32_e32 v26, v26
	v_mul_f32_e32 v29, 0x3fb8aa3b, v29
	v_exp_f32_e32 v29, v29
	v_mul_f32_e32 v32, 0x3fb8aa3b, v32
	v_exp_f32_e32 v32, v32
	v_mul_f32_e32 v30, 0x3fb8aa3b, v30
	v_exp_f32_e32 v30, v30
	v_mul_f32_e32 v35, 0x3fb8aa3b, v35
	v_exp_f32_e32 v35, v35
	v_mul_f32_e32 v28, 0x3fb8aa3b, v28
	v_exp_f32_e32 v28, v28
	v_mul_f32_e32 v38, 0x3fb8aa3b, v38
	v_exp_f32_e32 v38, v38
	v_mul_f32_e32 v40, 0x3fb8aa3b, v40
	v_exp_f32_e32 v40, v40
	v_mul_f32_e32 v42, 0x3fb8aa3b, v42
	v_exp_f32_e32 v42, v42
	v_mul_f32_e32 v25, 0x3fb8aa3b, v25
	v_exp_f32_e32 v25, v25
	v_mul_f32_e32 v45, 0x3fb8aa3b, v45
	v_exp_f32_e32 v45, v45
	v_mul_f32_e32 v47, 0x3fb8aa3b, v47
	v_exp_f32_e32 v47, v47
	v_mul_f32_e32 v49, 0x3fb8aa3b, v49
	v_exp_f32_e32 v49, v49
	v_mul_f32_e32 v51, 0x3fb8aa3b, v51
	v_exp_f32_e32 v51, v51
	v_mul_f32_e32 v53, 0x3fb8aa3b, v53
	v_exp_f32_e32 v53, v53
	v_mul_f32_e32 v55, 0x3fb8aa3b, v55
	v_exp_f32_e32 v55, v55
	v_mul_f32_e32 v57, 0x3fb8aa3b, v57
	v_exp_f32_e32 v57, v57
	v_mul_f32_e32 v59, 0x3fb8aa3b, v59
	v_exp_f32_e32 v59, v59
	v_mul_f32_e32 v61, 0x3fb8aa3b, v61
	v_exp_f32_e32 v61, v61
	v_mul_f32_e32 v63, 0x3fb8aa3b, v63
	v_exp_f32_e32 v63, v63
	v_mul_f32_e32 v65, 0x3fb8aa3b, v65
	v_exp_f32_e32 v65, v65
	v_mul_f32_e32 v67, 0x3fb8aa3b, v67
	v_exp_f32_e32 v67, v67
	v_mul_f32_e32 v69, 0x3fb8aa3b, v69
	v_exp_f32_e32 v69, v69
	v_mul_f32_e32 v71, 0x3fb8aa3b, v71
	v_exp_f32_e32 v71, v71
	v_mul_f32_e32 v24, 0x3fb8aa3b, v24
	v_exp_f32_e32 v24, v24
	v_mul_f32_e32 v23, 0x3fb8aa3b, v23
	v_exp_f32_e32 v23, v23
	v_mul_f32_e32 v113, 0x3fb8aa3b, v113
	v_exp_f32_e32 v113, v113
	v_mul_f32_e32 v112, 0x3fb8aa3b, v112
	v_exp_f32_e32 v112, v112
	v_mul_f32_e32 v111, 0x3fb8aa3b, v111
	v_exp_f32_e32 v111, v111
	v_mul_f32_e32 v110, 0x3fb8aa3b, v110
	v_exp_f32_e32 v110, v110
	v_mul_f32_e32 v109, 0x3fb8aa3b, v109
	v_exp_f32_e32 v109, v109
	v_mul_f32_e32 v108, 0x3fb8aa3b, v108
	v_exp_f32_e32 v108, v108
	v_mul_f32_e32 v107, 0x3fb8aa3b, v107
	v_exp_f32_e32 v107, v107
	v_mul_f32_e32 v105, 0x3fb8aa3b, v105
	v_exp_f32_e32 v105, v105
	v_mul_f32_e32 v104, 0x3fb8aa3b, v104
	v_exp_f32_e32 v104, v104
	v_mul_f32_e32 v103, 0x3fb8aa3b, v103
	v_exp_f32_e32 v103, v103
	v_mul_f32_e32 v102, 0x3fb8aa3b, v102
	v_exp_f32_e32 v102, v102
	v_mul_f32_e32 v101, 0x3fb8aa3b, v101
	v_exp_f32_e32 v101, v101
	v_mul_f32_e32 v100, 0x3fb8aa3b, v100
	v_exp_f32_e32 v100, v100
	v_mul_f32_e32 v99, 0x3fb8aa3b, v99
	v_exp_f32_e32 v99, v99
	v_mul_f32_e32 v22, 0x3fb8aa3b, v22
	v_exp_f32_e32 v22, v22
	v_mul_f32_e32 v21, 0x3fb8aa3b, v21
	v_exp_f32_e32 v21, v21
	v_mul_f32_e32 v98, 0x3fb8aa3b, v98
	v_exp_f32_e32 v98, v98
	v_mul_f32_e32 v97, 0x3fb8aa3b, v97
	v_exp_f32_e32 v97, v97
	v_mul_f32_e32 v96, 0x3fb8aa3b, v96
	v_exp_f32_e32 v96, v96
	v_mul_f32_e32 v95, 0x3fb8aa3b, v95
	v_exp_f32_e32 v95, v95
	v_mul_f32_e32 v94, 0x3fb8aa3b, v94
	v_exp_f32_e32 v94, v94
	v_mul_f32_e32 v93, 0x3fb8aa3b, v93
	v_exp_f32_e32 v93, v93
	v_mul_f32_e32 v92, 0x3fb8aa3b, v92
	v_exp_f32_e32 v92, v92
	v_mul_f32_e32 v91, 0x3fb8aa3b, v91
	v_exp_f32_e32 v91, v91
	v_mul_f32_e32 v90, 0x3fb8aa3b, v90
	v_exp_f32_e32 v90, v90
	v_mul_f32_e32 v89, 0x3fb8aa3b, v89
	v_exp_f32_e32 v89, v89
	v_mul_f32_e32 v88, 0x3fb8aa3b, v88
	v_exp_f32_e32 v88, v88
	v_mul_f32_e32 v87, 0x3fb8aa3b, v87
	v_exp_f32_e32 v87, v87
	v_mul_f32_e32 v86, 0x3fb8aa3b, v86
	v_exp_f32_e32 v86, v86
	v_mul_f32_e32 v85, 0x3fb8aa3b, v85
	v_exp_f32_e32 v85, v85
	v_mul_f32_e32 v144, 0x3fb8aa3b, v144
	v_exp_f32_e32 v144, v144
	s_branch .Lrc_join

; __device__ __forceinline__ float bf2f(bf16_t b) { return __uint_as_float((unsigned)b << 16); }
; __device__ __forceinline__ bf16_t f2bf(float f) { return (bf16_t)(pk2(f, 0.f) & 0xffffu); }
; __device__ __forceinline__ float fexp(float x) { return __expf(x); }
; __device__ __forceinline__ void gdn_unit(const Ctx& X, LAS unsigned char* hl, int b, int c, int h, int tid_h, int w4, int lane, int layer) {
;     ...
;     {
;         f32x4 acc[4];
;         const float eG63 = fexp(Gs[63]);
; #pragma unroll
;         for (int ct = 0; ct < 4; ++ct) acc[ct] = mma16(P, 16 * w4, WT, 16 * ct, (f32x4){0.f, 0.f, 0.f, 0.f}, r, q);
;         bf16_t* qe = WSP(bf16_t, WS_QEFF) + (size_t)uid * 4096;
; #pragma unroll
;         for (int ct = 0; ct < 4; ++ct)
; #pragma unroll
;             for (int j = 0; j < 4; ++j) { const int ii = 16 * w4 + 4 * q + j, col = 16 * ct + r;
;                 qe[ii * 64 + col] = f2bf(bf2f(Q[ii * LT + col]) * fexp(Gs[ii]) - acc[ct][j]); }
; #pragma unroll
;         for (int ct = 0; ct < 4; ++ct) acc[ct] = mma16(P, 16 * w4, UT, 16 * ct, (f32x4){0.f, 0.f, 0.f, 0.f}, r, q);
;         store_oloc(WSP(bf16_t, WS_OLOC), uid, w4, lane, acc);
; #pragma unroll
;         for (int ct = 0; ct < 4; ++ct) acc[ct] = mma16(KDT, 16 * w4, WT, 16 * ct, (f32x4){0.f, 0.f, 0.f, 0.f}, r, q);
;         bf16_t* mm = WSP(bf16_t, WS_MM) + (size_t)(uid - 2048) * 4096;
; #pragma unroll
;         for (int ct = 0; ct < 4; ++ct)
; #pragma unroll
;             for (int j = 0; j < 4; ++j) { const int ii = 16 * w4 + 4 * q + j, col = 16 * ct + r;
;                 mm[((w4 * 2 + (ct >> 1)) * 64 + (r >> 2) * 16 + 4 * q + j) * 8 + (ct & 1) * 4 + (r & 3)] = f2bf((ii == col ? eG63 : 0.f) - acc[ct][j]); }
; #pragma unroll
;         for (int ct = 0; ct < 4; ++ct) acc[ct] = mma16(KDT, 16 * w4, UT, 16 * ct, (f32x4){0.f, 0.f, 0.f, 0.f}, r, q);
;         store_bc(WSP(bf16_t, WS_BCS), uid, w4, r, q, acc);
;     }
.LBB0_619:
	s_waitcnt lgkmcnt(0)
	s_barrier
	v_bfe_u32 v54, v224, 6, 2
	v_and_b32_e32 v55, 15, v232
	v_lshrrev_b32_e32 v56, 4, v232
	v_lshl_or_b32 v57, v54, 4, v55
	v_mul_u32_u24_e32 v58, 0x90, v57
	v_mul_u32_u24_e32 v59, 0x90, v55
	v_lshl_add_u32 v60, v56, 4, v58
	v_lshl_add_u32 v61, v56, 4, v59
	v_add_u32_e32 v60, v182, v60
	v_add_u32_e32 v61, v182, v61
	v_add_u32_e32 v178, 0xb400, v60
	v_add_u32_e32 v179, 0x4800, v61
	v_add_u32_e32 v60, 0x9000, v60
	v_add_u32_e32 v61, 0x6c00, v61
	ds_read_b128 v[6:9], v178
	ds_read_b128 v[10:13], v178 offset:64
	ds_read_b128 v[22:25], v179
	ds_read_b128 v[26:29], v179 offset:64
	ds_read_b128 v[30:33], v179 offset:2304
	ds_read_b128 v[34:37], v179 offset:2368
	ds_read_b128 v[38:41], v179 offset:4608
	ds_read_b128 v[42:45], v179 offset:4672
	ds_read_b128 v[46:49], v179 offset:6912
	ds_read_b128 v[50:53], v179 offset:6976
	ds_read_b128 v[14:17], v60
	ds_read_b128 v[18:21], v60 offset:64
	v_lshl_add_u32 v62, v57, 2, v185
	v_lshl_add_u32 v63, v56, 3, v58
	v_add_u32_e32 v63, v182, v63
	ds_read_b32 v176, v62
	ds_read_b32 v177, v185 offset:252
	s_lshl_b32 s0, s22, 9
	s_lshl_b32 s1, s23, 7
	s_add_i32 s1, s1, s0
	s_or_b32 s0, s1, s21
	s_ashr_i32 s1, s0, 31
	s_lshl_b64 s[0:1], s[0:1], 13
	s_add_u32 s4, s89, s0
	s_addc_u32 s5, s78, s1
	s_add_u32 s6, s79, s0
	s_addc_u32 s7, s80, s1
	v_readlane_b32 s98, v253, 3
	v_readlane_b32 s99, v253, 4
	s_add_u32 s98, s98, s0
	s_addc_u32 s99, s99, s1
	s_add_u32 s98, s98, 0xff000000
	s_addc_u32 s99, s99, -1
	s_add_u32 s100, s74, s0
	s_addc_u32 s101, s75, s1
	v_readfirstlane_b32 s32, v54
	v_lshlrev_b32_e32 v64, 11, v54
	v_lshlrev_b32_e32 v65, 5, v232
	v_lshl_add_u32 v64, v232, 4, v64
	v_lshlrev_b32_e32 v66, 9, v54
	v_lshl_add_u32 v66, v232, 3, v66
	v_add_u32_e32 v67, 0x1000, v66
	v_lshlrev_b32_e32 v71, 7, v57
	v_lshl_add_u32 v71, v56, 3, v71
	v_lshlrev_b32_e32 v70, 2, v56
	v_sub_u32_e32 v70, v55, v70
	s_waitcnt lgkmcnt(4)
	v_mfma_f32_16x16x32_bf16 v[134:137], v[22:25], v[6:9], 0
	v_mfma_f32_16x16x32_bf16 v[138:141], v[30:33], v[6:9], 0
	v_mfma_f32_16x16x32_bf16 v[142:145], v[38:41], v[6:9], 0
	v_mfma_f32_16x16x32_bf16 v[146:149], v[46:49], v[6:9], 0
	v_mfma_f32_16x16x32_bf16 v[134:137], v[26:29], v[10:13], v[134:137]
	v_mfma_f32_16x16x32_bf16 v[138:141], v[34:37], v[10:13], v[138:141]
	v_mfma_f32_16x16x32_bf16 v[142:145], v[42:45], v[10:13], v[142:145]
	v_mfma_f32_16x16x32_bf16 v[146:149], v[50:53], v[10:13], v[146:149]
	ds_read_b64 v[150:151], v63
	ds_read_b64 v[152:153], v63 offset:32
	ds_read_b64 v[172:173], v63 offset:64
	ds_read_b64 v[174:175], v63 offset:96
	ds_read_b128 v[186:189], v61
	ds_read_b128 v[190:193], v61 offset:64
	ds_read_b128 v[194:197], v61 offset:2304
	ds_read_b128 v[198:201], v61 offset:2368
	ds_read_b128 v[202:205], v61 offset:4608
	ds_read_b128 v[206:209], v61 offset:4672
	ds_read_b128 v[210:213], v61 offset:6912
	s_waitcnt lgkmcnt(13)
	v_mfma_f32_16x16x32_bf16 v[236:239], v[22:25], v[14:17], 0
	v_mfma_f32_16x16x32_bf16 v[240:243], v[30:33], v[14:17], 0
	v_mfma_f32_16x16x32_bf16 v[244:247], v[38:41], v[14:17], 0
	v_mfma_f32_16x16x32_bf16 v[248:251], v[46:49], v[14:17], 0
	v_mfma_f32_16x16x32_bf16 v[236:239], v[26:29], v[18:21], v[236:239]
	v_mfma_f32_16x16x32_bf16 v[240:243], v[34:37], v[18:21], v[240:243]
	v_mfma_f32_16x16x32_bf16 v[244:247], v[42:45], v[18:21], v[244:247]
	v_mfma_f32_16x16x32_bf16 v[248:251], v[50:53], v[18:21], v[248:251]
	ds_read_b128 v[214:217], v61 offset:6976
	s_waitcnt lgkmcnt(8)
	v_mul_f32_e32 v176, 0x3fb8aa3b, v176
	v_mul_f32_e32 v177, 0x3fb8aa3b, v177
	v_exp_f32_e32 v176, v176
	v_exp_f32_e32 v177, v177
	v_cmp_eq_u32_e32 vcc, 0, v70
	v_cmp_eq_u32_e64 s[0:1], 1, v70
	v_lshlrev_b32_e32 v76, 16, v150
	v_and_b32_e32 v77, 0xffff0000, v150
	v_cndmask_b32_e32 v72, 0, v177, vcc
	v_cndmask_b32_e64 v73, 0, v177, s[0:1]
	v_cmp_eq_u32_e32 vcc, 2, v70
	v_cmp_eq_u32_e64 s[0:1], 3, v70
	v_lshlrev_b32_e32 v78, 16, v151
	v_and_b32_e32 v79, 0xffff0000, v151
	v_cndmask_b32_e32 v74, 0, v177, vcc
	v_cndmask_b32_e64 v75, 0, v177, s[0:1]
	s_waitcnt lgkmcnt(0)
	v_mfma_f32_16x16x32_bf16 v[84:87], v[6:9], v[186:189], 0
	v_mfma_f32_16x16x32_bf16 v[88:91], v[6:9], v[194:197], 0
	v_mfma_f32_16x16x32_bf16 v[92:95], v[6:9], v[202:205], 0
	v_mfma_f32_16x16x32_bf16 v[96:99], v[6:9], v[210:213], 0
	v_mfma_f32_16x16x32_bf16 v[114:117], v[14:17], v[186:189], 0
	v_mfma_f32_16x16x32_bf16 v[118:121], v[14:17], v[194:197], 0
	v_mfma_f32_16x16x32_bf16 v[122:125], v[14:17], v[202:205], 0
	v_mfma_f32_16x16x32_bf16 v[126:129], v[14:17], v[210:213], 0
	v_mfma_f32_16x16x32_bf16 v[84:87], v[10:13], v[190:193], v[84:87]
	v_mfma_f32_16x16x32_bf16 v[88:91], v[10:13], v[198:201], v[88:91]
	v_mfma_f32_16x16x32_bf16 v[92:95], v[10:13], v[206:209], v[92:95]
	v_mfma_f32_16x16x32_bf16 v[96:99], v[10:13], v[214:217], v[96:99]
	v_mfma_f32_16x16x32_bf16 v[114:117], v[18:21], v[190:193], v[114:117]
	v_mfma_f32_16x16x32_bf16 v[118:121], v[18:21], v[198:201], v[118:121]
	v_mfma_f32_16x16x32_bf16 v[122:125], v[18:21], v[206:209], v[122:125]
	v_mfma_f32_16x16x32_bf16 v[126:129], v[18:21], v[214:217], v[126:129]
	v_fma_f32 v76, v176, v76, -v134
	v_fma_f32 v77, v176, v77, -v135
	v_fma_f32 v78, v176, v78, -v136
	v_fma_f32 v79, v176, v79, -v137
	v_cvt_pk_bf16_f32 v218, v76, v77
	v_cvt_pk_bf16_f32 v219, v78, v79
	global_store_dwordx2 v71, v[218:219], s[4:5]
	v_lshlrev_b32_e32 v76, 16, v152
	v_and_b32_e32 v77, 0xffff0000, v152
	v_lshlrev_b32_e32 v78, 16, v153
	v_and_b32_e32 v79, 0xffff0000, v153
	v_fma_f32 v76, v176, v76, -v138
	v_fma_f32 v77, v176, v77, -v139
	v_fma_f32 v78, v176, v78, -v140
	v_fma_f32 v79, v176, v79, -v141
	v_cvt_pk_bf16_f32 v220, v76, v77
	v_cvt_pk_bf16_f32 v221, v78, v79
; __device__ __forceinline__ bf16_t f2bf(float f) { return (bf16_t)(pk2(f, 0.f) & 0xffffu); }
; #define LBAR() do { asm volatile("s_waitcnt lgkmcnt(0)" ::: "memory"); __builtin_amdgcn_s_barrier(); asm volatile("" ::: "memory"); } while (0)
; __device__ __forceinline__ void gdn_unit(const Ctx& X, LAS unsigned char* hl, int b, int c, int h, int tid_h, int w4, int lane, int layer) {
;     ...
;         bf16_t* mm = WSP(bf16_t, WS_MM) + (size_t)(uid - 2048) * 4096;
; #pragma unroll
;         for (int ct = 0; ct < 4; ++ct)
; #pragma unroll
;             for (int j = 0; j < 4; ++j) { const int ii = 16 * w4 + 4 * q + j, col = 16 * ct + r;
;                 mm[((w4 * 2 + (ct >> 1)) * 64 + (r >> 2) * 16 + 4 * q + j) * 8 + (ct & 1) * 4 + (r & 3)] = f2bf((ii == col ? eG63 : 0.f) - acc[ct][j]); }
; #pragma unroll
;         for (int ct = 0; ct < 4; ++ct) acc[ct] = mma16(KDT, 16 * w4, UT, 16 * ct, (f32x4){0.f, 0.f, 0.f, 0.f}, r, q);
;         store_bc(WSP(bf16_t, WS_BCS), uid, w4, r, q, acc);
;     }
;     LBAR();
	global_store_dwordx2 v71, v[220:221], s[4:5] offset:32
	v_lshlrev_b32_e32 v76, 16, v172
	v_and_b32_e32 v77, 0xffff0000, v172
	v_lshlrev_b32_e32 v78, 16, v173
	v_and_b32_e32 v79, 0xffff0000, v173
	v_fma_f32 v76, v176, v76, -v142
	v_fma_f32 v77, v176, v77, -v143
	v_fma_f32 v78, v176, v78, -v144
	v_fma_f32 v79, v176, v79, -v145
	v_cvt_pk_bf16_f32 v222, v76, v77
	v_cvt_pk_bf16_f32 v223, v78, v79
	global_store_dwordx2 v71, v[222:223], s[4:5] offset:64
	v_lshlrev_b32_e32 v76, 16, v174
	v_and_b32_e32 v77, 0xffff0000, v174
	v_lshlrev_b32_e32 v78, 16, v175
	v_and_b32_e32 v79, 0xffff0000, v175
	v_fma_f32 v76, v176, v76, -v146
	v_fma_f32 v77, v176, v77, -v147
	v_fma_f32 v78, v176, v78, -v148
	v_fma_f32 v79, v176, v79, -v149
	v_cvt_pk_bf16_f32 v226, v76, v77
	v_cvt_pk_bf16_f32 v227, v78, v79
	global_store_dwordx2 v71, v[226:227], s[4:5] offset:96
	s_cmp_eq_u32 s32, 0
	s_cselect_b32 s0, 1.0, 0
	v_fma_f32 v76, v72, s0, -v236
	v_fma_f32 v77, v73, s0, -v237
	v_fma_f32 v78, v74, s0, -v238
	v_fma_f32 v79, v75, s0, -v239
	v_cvt_pk_bf16_f32 v100, v76, v77
	v_cvt_pk_bf16_f32 v101, v78, v79
	s_cmp_eq_u32 s32, 1
	s_cselect_b32 s0, 1.0, 0
	v_fma_f32 v76, v72, s0, -v240
	v_fma_f32 v77, v73, s0, -v241
	v_fma_f32 v78, v74, s0, -v242
	v_fma_f32 v79, v75, s0, -v243
	v_cvt_pk_bf16_f32 v102, v76, v77
	v_cvt_pk_bf16_f32 v103, v78, v79
	global_store_dwordx4 v64, v[100:103], s[98:99]
	s_cmp_eq_u32 s32, 2
	s_cselect_b32 s0, 1.0, 0
	v_fma_f32 v76, v72, s0, -v244
	v_fma_f32 v77, v73, s0, -v245
	v_fma_f32 v78, v74, s0, -v246
	v_fma_f32 v79, v75, s0, -v247
	v_cvt_pk_bf16_f32 v104, v76, v77
	v_cvt_pk_bf16_f32 v105, v78, v79
	s_cmp_eq_u32 s32, 3
	s_cselect_b32 s0, 1.0, 0
	v_fma_f32 v76, v72, s0, -v248
	v_fma_f32 v77, v73, s0, -v249
	v_fma_f32 v78, v74, s0, -v250
	v_fma_f32 v79, v75, s0, -v251
	v_cvt_pk_bf16_f32 v106, v76, v77
	v_cvt_pk_bf16_f32 v107, v78, v79
	global_store_dwordx4 v64, v[104:107], s[98:99] offset:1024
	v_cvt_pk_bf16_f32 v108, v84, v85
	v_cvt_pk_bf16_f32 v109, v86, v87
	v_cvt_pk_bf16_f32 v110, v88, v89
	v_cvt_pk_bf16_f32 v111, v90, v91
	global_store_dwordx4 v65, v[108:111], s[6:7] nt
	v_cvt_pk_bf16_f32 v80, v92, v93
	v_cvt_pk_bf16_f32 v81, v94, v95
	v_cvt_pk_bf16_f32 v82, v96, v97
	v_cvt_pk_bf16_f32 v83, v98, v99
	global_store_dwordx4 v65, v[80:83], s[6:7] offset:16 nt
	v_cvt_pk_bf16_f32 v40, v114, v115
	v_cvt_pk_bf16_f32 v41, v116, v117
	global_store_dwordx2 v66, v[40:41], s[100:101]
	v_cvt_pk_bf16_f32 v42, v118, v119
	v_cvt_pk_bf16_f32 v43, v120, v121
	global_store_dwordx2 v66, v[42:43], s[100:101] offset:2048
	v_cvt_pk_bf16_f32 v44, v122, v123
	v_cvt_pk_bf16_f32 v45, v124, v125
	global_store_dwordx2 v67, v[44:45], s[100:101]
	v_cvt_pk_bf16_f32 v46, v126, v127
	v_cvt_pk_bf16_f32 v47, v128, v129
	global_store_dwordx2 v67, v[46:47], s[100:101] offset:2048
	s_branch .Lgdn_p4_pad_end
	s_nop 0
	s_nop 0
	s_nop 0
	s_nop 0
	s_nop 0
	s_nop 0
	s_nop 0
	s_nop 0
	s_nop 0
	s_nop 0
	s_nop 0
	s_nop 0
	s_nop 0
	s_nop 0
	s_nop 0
	s_nop 0
	s_nop 0
	s_nop 0
	s_nop 0
	s_nop 0
	s_nop 0
	s_nop 0
	s_nop 0
	s_nop 0
	s_nop 0
	s_nop 0
	s_nop 0
	s_nop 0
	s_nop 0
	s_nop 0
	s_nop 0
	s_nop 0
	s_nop 0
	s_nop 0
	s_nop 0
	s_nop 0
	s_nop 0
	s_nop 0
	s_nop 0
	s_nop 0
	s_nop 0
	s_nop 0
	s_nop 0
	s_nop 0
	s_nop 0
	s_nop 0
	s_nop 0
	s_nop 0
	s_nop 0
	s_nop 0
	s_nop 0
	s_nop 0
	s_nop 0
	s_nop 0
	s_nop 0
	s_nop 0
	s_nop 0
	s_nop 0
	s_nop 0
	s_nop 0
	s_nop 0
	s_nop 0
	s_nop 0
	s_nop 0
	s_nop 0
	s_nop 0
	s_nop 0
	s_nop 0
	s_nop 0
	s_nop 0
	s_nop 0
	s_nop 0
	s_nop 0
	s_nop 0
	s_nop 0
	s_nop 0
	s_nop 0
	s_nop 0
	s_nop 0
	s_nop 0
	s_nop 0
	s_nop 0
	s_nop 0
	s_nop 0
	s_nop 0
	s_nop 0
	s_nop 0
	s_nop 0
	s_nop 0
	s_nop 0
	s_nop 0
	s_nop 0
	s_nop 0
	s_nop 0
	s_nop 0
	s_nop 0
	s_nop 0
	s_nop 0
	s_nop 0
	s_nop 0
	s_nop 0
	s_nop 0
	s_nop 0
	s_nop 0
	s_nop 0
	s_nop 0
	s_nop 0
	s_nop 0
	s_nop 0
	s_nop 0
	s_nop 0
	s_nop 0
	s_nop 0
	s_nop 0
	s_nop 0
	s_nop 0
	s_nop 0
	s_nop 0
	s_nop 0
	s_nop 0
	s_nop 0
	s_nop 0
	s_nop 0
	s_nop 0
	s_nop 0
	s_nop 0
	s_nop 0
	s_nop 0
	s_nop 0
	s_nop 0
	s_nop 0
	s_nop 0
	s_nop 0
	s_nop 0
	s_nop 0
	s_nop 0
	s_nop 0
	s_nop 0
	s_nop 0
	s_nop 0
	s_nop 0
	s_nop 0
	s_nop 0
	s_nop 0
	s_nop 0
	s_nop 0
	s_nop 0
	s_nop 0
	s_nop 0
	s_nop 0
	s_nop 0
	s_nop 0
	s_nop 0
	s_nop 0
	s_nop 0
	s_nop 0
	s_nop 0
	s_nop 0
	s_nop 0
	s_nop 0
	s_nop 0
	s_nop 0
	s_nop 0
	s_nop 0
	s_nop 0
	s_nop 0
	s_nop 0
	s_nop 0
	s_nop 0
	s_nop 0
	s_nop 0
	s_nop 0
	s_nop 0
	s_nop 0
	s_nop 0
	s_nop 0
	s_nop 0
	s_nop 0
	s_nop 0
	s_nop 0
	s_nop 0
	s_nop 0
	s_nop 0
	s_nop 0
	s_nop 0
	s_nop 0
	s_nop 0
	s_nop 0
	s_nop 0
	s_nop 0
	s_nop 0
	s_nop 0
	s_nop 0
	s_nop 0
	s_nop 0
	s_nop 0
	s_nop 0
	s_nop 0
	s_nop 0
	s_nop 0
	s_nop 0
	s_nop 0
	s_nop 0
	s_nop 0
	s_nop 0
	s_nop 0
	s_nop 0
	s_nop 0
	s_nop 0
	s_nop 0
	s_nop 0
	s_nop 0
	s_nop 0
	s_nop 0
	s_nop 0
	s_nop 0
	s_nop 0
	s_nop 0
	s_nop 0
	s_nop 0
	s_nop 0
	s_nop 0
	s_nop 0
	s_nop 0
	s_nop 0
	s_nop 0
	s_nop 0
	s_nop 0
	s_nop 0
	s_nop 0
	s_nop 0
	s_nop 0
	s_nop 0
	s_nop 0
	s_nop 0
	s_nop 0
	s_nop 0
	s_nop 0
	s_nop 0
	s_nop 0
	s_nop 0
	s_nop 0
	s_nop 0
	s_nop 0
	s_nop 0
	s_nop 0
	s_nop 0
	s_nop 0
	s_nop 0
	s_nop 0
	s_nop 0
	s_nop 0
	s_nop 0
	s_nop 0
	s_nop 0
	s_nop 0
	s_nop 0
	s_nop 0
	s_nop 0
	s_nop 0
	s_nop 0
	s_nop 0
	s_nop 0
	s_nop 0
	s_nop 0
	s_nop 0
	s_nop 0
	s_nop 0
	s_nop 0
	s_nop 0
	s_nop 0
	s_nop 0
	s_nop 0
	s_nop 0
	s_nop 0
	s_nop 0
	s_nop 0
	s_nop 0
	s_nop 0
	s_nop 0
	s_nop 0
	s_nop 0
	s_nop 0
	s_nop 0
	s_nop 0
	s_nop 0
	s_nop 0
	s_nop 0
	s_nop 0
	s_nop 0
	s_nop 0
	s_nop 0
	s_nop 0
	s_nop 0
	s_nop 0
	s_nop 0
	s_nop 0
	s_nop 0
	s_nop 0
	s_nop 0
	s_nop 0
	s_nop 0
	s_nop 0
	s_nop 0
	s_nop 0
	s_nop 0
	s_nop 0
	s_nop 0
	s_nop 0
	s_nop 0
	s_nop 0
	s_nop 0
	s_nop 0
	s_nop 0
	s_nop 0
	s_nop 0
	s_nop 0
	s_nop 0
	s_nop 0
	s_nop 0
	s_nop 0
	s_nop 0
	s_nop 0
	s_nop 0
	s_nop 0
	s_nop 0
	s_nop 0
	s_nop 0
	s_nop 0
	s_nop 0
	s_nop 0
	s_nop 0
	s_nop 0
	s_nop 0
	s_nop 0
	s_nop 0
	s_nop 0
.Lgdn_p4_pad_end:
	s_waitcnt lgkmcnt(0)
	s_barrier
	s_mov_b64 s[0:1], 0
